# SCAN rewrite made grid-size independent (grid-stride over chain units)
# baseline (speedup 1.0000x reference)
.LBB1_811:
	s_and_b64 vcc, exec, s[30:31]
	s_cbranch_vccz .LBB1_861
	s_mov_b64 exec, -1
	v_lshrrev_b32_e32 v220, 6, v162
	v_readlane_b32 s2, v242, 0
	s_load_dwordx4 s[64:67], s[0:1], 0x178
	s_load_dwordx4 s[68:71], s[0:1], 0x188
	s_load_dwordx4 s[72:75], s[0:1], 0x198
	v_readfirstlane_b32 s4, v220
	s_cmp_lt_u32 s4, 2
	s_cbranch_scc0 .Lgs_notc
	s_lshl_b32 s5, s2, 1
	s_add_u32 s76, s5, s4
	v_readlane_b32 s77, v241, 24
	s_lshr_b32 s77, s77, 1
	s_cmp_lt_u32 s76, 1024
	s_cbranch_scc0 .Lgs_done
.Lgs_unit:
	s_mov_b32 s5, s76
	s_lshr_b32 s6, s5, 5
	s_and_b32 s5, s5, 31
	s_lshl_b32 s5, s5, 6
	v_add_u32_e32 v236, s5, v168
	v_lshlrev_b32_e32 v236, 4, v236
	s_lshr_b32 s7, s6, 4
	s_and_b32 s8, s6, 15
	s_mul_i32 s8, s8, 66
	s_mul_i32 s9, s7, 1056
	s_add_u32 s8, s8, s9
	s_cmp_eq_u32 s7, 0
	s_cselect_b32 s9, 64, 65
	s_cselect_b32 s10, 1, -1
	s_mov_b32 s11, 0x7fff0000
	s_movk_i32 s14, 66
	s_cselect_b32 s11, s14, s11
	s_add_u32 s9, s9, s8
	s_add_u32 s11, s11, s8
	v_cmp_gt_u32_e32 vcc, 2, v168
	v_add_u32_e32 v220, 64, v168
	v_add_u32_e32 v221, -2, v168
	v_cndmask_b32_e32 v220, v221, v220, vcc
	v_sub_u32_e32 v221, 65, v168
	s_cmp_eq_u32 s7, 0
	s_cselect_b64 s[18:19], -1, 0
	v_and_b32_e32 v222, 1, v168
	v_cndmask_b32_e64 v220, v221, v220, s[18:19]
	v_add_u32_e32 v223, 62, v222
	v_sub_u32_e32 v224, 1, v222
	v_cndmask_b32_e64 v223, v224, v223, s[18:19]
	v_add_u32_e32 v220, s8, v220
	v_add_u32_e32 v223, s8, v223
	v_lshlrev_b32_e32 v220, 3, v220
	v_lshlrev_b32_e32 v223, 3, v223
	s_waitcnt lgkmcnt(0)
	global_load_dwordx2 v[232:233], v220, s[72:73]
	global_load_dwordx2 v[234:235], v223, s[72:73]
	v_mov_b32_e32 v0, 0
	v_mov_b32_e32 v1, 0
	v_mov_b32_e32 v2, 0
	v_mov_b32_e32 v3, 0
	v_mov_b32_e32 v4, 0
	v_mov_b32_e32 v5, 0
	v_mov_b32_e32 v6, 0
	v_mov_b32_e32 v7, 0
	v_mov_b32_e32 v228, 0xf149f2ca
	s_waitcnt lgkmcnt(0)
	s_mov_b32 s12, s9
	s_mov_b32 s13, s9
	s_lshl_b32 s14, s12, 15
	s_add_u32 s16, s64, s14
	s_addc_u32 s17, s65, 0
	global_load_dwordx4 v[8:11], v236, s[16:17]
	s_add_i32 s12, s12, s10
	s_cmp_eq_u32 s12, s11
	s_cselect_b32 s12, s8, s12
	s_lshl_b32 s14, s12, 15
	s_add_u32 s16, s64, s14
	s_addc_u32 s17, s65, 0
	global_load_dwordx4 v[12:15], v236, s[16:17]
	s_add_i32 s12, s12, s10
	s_cmp_eq_u32 s12, s11
	s_cselect_b32 s12, s8, s12
	s_lshl_b32 s14, s12, 15
	s_add_u32 s16, s64, s14
	s_addc_u32 s17, s65, 0
	global_load_dwordx4 v[16:19], v236, s[16:17]
	s_add_i32 s12, s12, s10
	s_cmp_eq_u32 s12, s11
	s_cselect_b32 s12, s8, s12
	s_lshl_b32 s14, s12, 15
	s_add_u32 s16, s64, s14
	s_addc_u32 s17, s65, 0
	global_load_dwordx4 v[20:23], v236, s[16:17]
	s_add_i32 s12, s12, s10
	s_cmp_eq_u32 s12, s11
	s_cselect_b32 s12, s8, s12
	s_lshl_b32 s14, s12, 15
	s_add_u32 s16, s64, s14
	s_addc_u32 s17, s65, 0
	global_load_dwordx4 v[24:27], v236, s[16:17]
	s_add_i32 s12, s12, s10
	s_cmp_eq_u32 s12, s11
	s_cselect_b32 s12, s8, s12
	s_lshl_b32 s14, s12, 15
	s_add_u32 s16, s64, s14
	s_addc_u32 s17, s65, 0
	global_load_dwordx4 v[28:31], v236, s[16:17]
	s_add_i32 s12, s12, s10
	s_cmp_eq_u32 s12, s11
	s_cselect_b32 s12, s8, s12
	s_lshl_b32 s14, s12, 15
	s_add_u32 s16, s64, s14
	s_addc_u32 s17, s65, 0
	global_load_dwordx4 v[32:35], v236, s[16:17]
	s_add_i32 s12, s12, s10
	s_cmp_eq_u32 s12, s11
	s_cselect_b32 s12, s8, s12
	s_lshl_b32 s14, s12, 15
	s_add_u32 s16, s64, s14
	s_addc_u32 s17, s65, 0
	global_load_dwordx4 v[36:39], v236, s[16:17]
	s_add_i32 s12, s12, s10
	s_cmp_eq_u32 s12, s11
	s_cselect_b32 s12, s8, s12
	s_lshl_b32 s14, s12, 15
	s_add_u32 s16, s64, s14
	s_addc_u32 s17, s65, 0
	global_load_dwordx4 v[40:43], v236, s[16:17]
	s_add_i32 s12, s12, s10
	s_cmp_eq_u32 s12, s11
	s_cselect_b32 s12, s8, s12
	s_lshl_b32 s14, s12, 15
	s_add_u32 s16, s64, s14
	s_addc_u32 s17, s65, 0
	global_load_dwordx4 v[44:47], v236, s[16:17]
	s_add_i32 s12, s12, s10
	s_cmp_eq_u32 s12, s11
	s_cselect_b32 s12, s8, s12
	s_lshl_b32 s14, s12, 15
	s_add_u32 s16, s64, s14
	s_addc_u32 s17, s65, 0
	global_load_dwordx4 v[48:51], v236, s[16:17]
	s_add_i32 s12, s12, s10
	s_cmp_eq_u32 s12, s11
	s_cselect_b32 s12, s8, s12
	s_lshl_b32 s14, s12, 15
	s_add_u32 s16, s64, s14
	s_addc_u32 s17, s65, 0
	global_load_dwordx4 v[52:55], v236, s[16:17]
	s_add_i32 s12, s12, s10
	s_cmp_eq_u32 s12, s11
	s_cselect_b32 s12, s8, s12
	s_lshl_b32 s14, s12, 15
	s_add_u32 s16, s64, s14
	s_addc_u32 s17, s65, 0
	global_load_dwordx4 v[56:59], v236, s[16:17]
	s_add_i32 s12, s12, s10
	s_cmp_eq_u32 s12, s11
	s_cselect_b32 s12, s8, s12
	s_lshl_b32 s14, s12, 15
	s_add_u32 s16, s64, s14
	s_addc_u32 s17, s65, 0
	global_load_dwordx4 v[60:63], v236, s[16:17]
	s_add_i32 s12, s12, s10
	s_cmp_eq_u32 s12, s11
	s_cselect_b32 s12, s8, s12
	s_lshl_b32 s14, s12, 15
	s_add_u32 s16, s64, s14
	s_addc_u32 s17, s65, 0
	global_load_dwordx4 v[64:67], v236, s[16:17]
	s_add_i32 s12, s12, s10
	s_cmp_eq_u32 s12, s11
	s_cselect_b32 s12, s8, s12
	s_lshl_b32 s14, s12, 15
	s_add_u32 s16, s64, s14
	s_addc_u32 s17, s65, 0
	global_load_dwordx4 v[68:71], v236, s[16:17]
	s_add_i32 s12, s12, s10
	s_cmp_eq_u32 s12, s11
	s_cselect_b32 s12, s8, s12
	s_lshl_b32 s14, s12, 15
	s_add_u32 s16, s64, s14
	s_addc_u32 s17, s65, 0
	global_load_dwordx4 v[72:75], v236, s[16:17]
	s_add_i32 s12, s12, s10
	s_cmp_eq_u32 s12, s11
	s_cselect_b32 s12, s8, s12
	s_lshl_b32 s14, s12, 15
	s_add_u32 s16, s64, s14
	s_addc_u32 s17, s65, 0
	global_load_dwordx4 v[76:79], v236, s[16:17]
	s_add_i32 s12, s12, s10
	s_cmp_eq_u32 s12, s11
	s_cselect_b32 s12, s8, s12
	s_lshl_b32 s14, s12, 15
	s_add_u32 s16, s64, s14
	s_addc_u32 s17, s65, 0
	global_load_dwordx4 v[80:83], v236, s[16:17]
	s_add_i32 s12, s12, s10
	s_cmp_eq_u32 s12, s11
	s_cselect_b32 s12, s8, s12
	s_lshl_b32 s14, s12, 15
	s_add_u32 s16, s64, s14
	s_addc_u32 s17, s65, 0
	global_load_dwordx4 v[84:87], v236, s[16:17]
	s_add_i32 s12, s12, s10
	s_cmp_eq_u32 s12, s11
	s_cselect_b32 s12, s8, s12
	s_lshl_b32 s14, s12, 15
	s_add_u32 s16, s64, s14
	s_addc_u32 s17, s65, 0
	global_load_dwordx4 v[88:91], v236, s[16:17]
	s_add_i32 s12, s12, s10
	s_cmp_eq_u32 s12, s11
	s_cselect_b32 s12, s8, s12
	s_lshl_b32 s14, s12, 15
	s_add_u32 s16, s64, s14
	s_addc_u32 s17, s65, 0
	global_load_dwordx4 v[92:95], v236, s[16:17]
	s_add_i32 s12, s12, s10
	s_cmp_eq_u32 s12, s11
	s_cselect_b32 s12, s8, s12
	s_lshl_b32 s14, s12, 15
	s_add_u32 s16, s64, s14
	s_addc_u32 s17, s65, 0
	global_load_dwordx4 v[96:99], v236, s[16:17]
	s_add_i32 s12, s12, s10
	s_cmp_eq_u32 s12, s11
	s_cselect_b32 s12, s8, s12
	s_lshl_b32 s14, s12, 15
	s_add_u32 s16, s64, s14
	s_addc_u32 s17, s65, 0
	global_load_dwordx4 v[100:103], v236, s[16:17]
	s_add_i32 s12, s12, s10
	s_cmp_eq_u32 s12, s11
	s_cselect_b32 s12, s8, s12
	s_lshl_b32 s14, s12, 15
	s_add_u32 s16, s64, s14
	s_addc_u32 s17, s65, 0
	global_load_dwordx4 v[104:107], v236, s[16:17]
	s_add_i32 s12, s12, s10
	s_cmp_eq_u32 s12, s11
	s_cselect_b32 s12, s8, s12
	s_lshl_b32 s14, s12, 15
	s_add_u32 s16, s64, s14
	s_addc_u32 s17, s65, 0
	global_load_dwordx4 v[108:111], v236, s[16:17]
	s_add_i32 s12, s12, s10
	s_cmp_eq_u32 s12, s11
	s_cselect_b32 s12, s8, s12
	s_lshl_b32 s14, s12, 15
	s_add_u32 s16, s64, s14
	s_addc_u32 s17, s65, 0
	global_load_dwordx4 v[112:115], v236, s[16:17]
	s_add_i32 s12, s12, s10
	s_cmp_eq_u32 s12, s11
	s_cselect_b32 s12, s8, s12
	s_lshl_b32 s14, s12, 15
	s_add_u32 s16, s64, s14
	s_addc_u32 s17, s65, 0
	global_load_dwordx4 v[116:119], v236, s[16:17]
	s_add_i32 s12, s12, s10
	s_cmp_eq_u32 s12, s11
	s_cselect_b32 s12, s8, s12
	s_lshl_b32 s14, s12, 15
	s_add_u32 s16, s64, s14
	s_addc_u32 s17, s65, 0
	global_load_dwordx4 v[120:123], v236, s[16:17]
	s_add_i32 s12, s12, s10
	s_cmp_eq_u32 s12, s11
	s_cselect_b32 s12, s8, s12
	s_lshl_b32 s14, s12, 15
	s_add_u32 s16, s64, s14
	s_addc_u32 s17, s65, 0
	global_load_dwordx4 v[124:127], v236, s[16:17]
	s_add_i32 s12, s12, s10
	s_cmp_eq_u32 s12, s11
	s_cselect_b32 s12, s8, s12
	s_lshl_b32 s14, s12, 15
	s_add_u32 s16, s64, s14
	s_addc_u32 s17, s65, 0
	global_load_dwordx4 v[130:133], v236, s[16:17]
	s_add_i32 s12, s12, s10
	s_cmp_eq_u32 s12, s11
	s_cselect_b32 s12, s8, s12
	s_lshl_b32 s14, s12, 15
	s_add_u32 s16, s64, s14
	s_addc_u32 s17, s65, 0
	global_load_dwordx4 v[134:137], v236, s[16:17]
	s_add_i32 s12, s12, s10
	s_cmp_eq_u32 s12, s11
	s_cselect_b32 s12, s8, s12
	s_lshl_b32 s14, s12, 15
	s_add_u32 s16, s64, s14
	s_addc_u32 s17, s65, 0
	global_load_dwordx4 v[138:141], v236, s[16:17]
	s_add_i32 s12, s12, s10
	s_cmp_eq_u32 s12, s11
	s_cselect_b32 s12, s8, s12
	s_lshl_b32 s14, s12, 15
	s_add_u32 s16, s64, s14
	s_addc_u32 s17, s65, 0
	global_load_dwordx4 v[142:145], v236, s[16:17]
	s_add_i32 s12, s12, s10
	s_cmp_eq_u32 s12, s11
	s_cselect_b32 s12, s8, s12
	s_lshl_b32 s14, s12, 15
	s_add_u32 s16, s64, s14
	s_addc_u32 s17, s65, 0
	global_load_dwordx4 v[146:149], v236, s[16:17]
	s_add_i32 s12, s12, s10
	s_cmp_eq_u32 s12, s11
	s_cselect_b32 s12, s8, s12
	s_lshl_b32 s14, s12, 15
	s_add_u32 s16, s64, s14
	s_addc_u32 s17, s65, 0
	global_load_dwordx4 v[150:153], v236, s[16:17]
	s_add_i32 s12, s12, s10
	s_cmp_eq_u32 s12, s11
	s_cselect_b32 s12, s8, s12
	s_lshl_b32 s14, s12, 15
	s_add_u32 s16, s64, s14
	s_addc_u32 s17, s65, 0
	global_load_dwordx4 v[154:157], v236, s[16:17]
	s_add_i32 s12, s12, s10
	s_cmp_eq_u32 s12, s11
	s_cselect_b32 s12, s8, s12
	s_lshl_b32 s14, s12, 15
	s_add_u32 s16, s64, s14
	s_addc_u32 s17, s65, 0
	global_load_dwordx4 v[158:161], v236, s[16:17]
	s_add_i32 s12, s12, s10
	s_cmp_eq_u32 s12, s11
	s_cselect_b32 s12, s8, s12
	s_lshl_b32 s14, s12, 15
	s_add_u32 s16, s64, s14
	s_addc_u32 s17, s65, 0
	global_load_dwordx4 v[188:191], v236, s[16:17]
	s_add_i32 s12, s12, s10
	s_cmp_eq_u32 s12, s11
	s_cselect_b32 s12, s8, s12
	s_lshl_b32 s14, s12, 15
	s_add_u32 s16, s64, s14
	s_addc_u32 s17, s65, 0
	global_load_dwordx4 v[192:195], v236, s[16:17]
	s_add_i32 s12, s12, s10
	s_cmp_eq_u32 s12, s11
	s_cselect_b32 s12, s8, s12
	s_lshl_b32 s14, s12, 15
	s_add_u32 s16, s64, s14
	s_addc_u32 s17, s65, 0
	global_load_dwordx4 v[196:199], v236, s[16:17]
	s_add_i32 s12, s12, s10
	s_cmp_eq_u32 s12, s11
	s_cselect_b32 s12, s8, s12
	s_lshl_b32 s14, s12, 15
	s_add_u32 s16, s64, s14
	s_addc_u32 s17, s65, 0
	global_load_dwordx4 v[200:203], v236, s[16:17]
	s_add_i32 s12, s12, s10
	s_cmp_eq_u32 s12, s11
	s_cselect_b32 s12, s8, s12
	s_lshl_b32 s14, s12, 15
	s_add_u32 s16, s64, s14
	s_addc_u32 s17, s65, 0
	global_load_dwordx4 v[204:207], v236, s[16:17]
	s_add_i32 s12, s12, s10
	s_cmp_eq_u32 s12, s11
	s_cselect_b32 s12, s8, s12
	s_lshl_b32 s14, s12, 15
	s_add_u32 s16, s64, s14
	s_addc_u32 s17, s65, 0
	global_load_dwordx4 v[208:211], v236, s[16:17]
	s_add_i32 s12, s12, s10
	s_cmp_eq_u32 s12, s11
	s_cselect_b32 s12, s8, s12
	s_waitcnt vmcnt(22)
	v_cvt_pk_bf16_f32 v216, v0, v1
	v_cvt_pk_bf16_f32 v217, v2, v3
	v_cvt_pk_bf16_f32 v218, v4, v5
	v_cvt_pk_bf16_f32 v219, v6, v7
	s_lshl_b32 s14, s13, 15
	s_add_u32 s16, s66, s14
	s_addc_u32 s17, s67, 0
	global_store_dwordx4 v236, v[216:219], s[16:17]
	v_readlane_b32 s18, v232, 0
	v_readlane_b32 s19, v233, 0
	s_nop 1
	v_add_f32_e32 v231, s18, v228
	v_max_f32_e32 v228, s19, v231
	v_sub_f32_e32 v231, v231, v228
	v_sub_f32_e32 v229, s19, v228
	v_mul_f32_e32 v231, 0x3fb8aa3b, v231
	v_mul_f32_e32 v229, 0x3fb8aa3b, v229
	v_exp_f32_e32 v230, v229
	v_exp_f32_e32 v229, v231
	s_nop 0
	v_lshlrev_b32_e32 v220, 16, v8
	v_and_b32_e32 v221, 0xffff0000, v8
	v_lshlrev_b32_e32 v222, 16, v9
	v_and_b32_e32 v223, 0xffff0000, v9
	v_lshlrev_b32_e32 v224, 16, v10
	v_and_b32_e32 v225, 0xffff0000, v10
	v_lshlrev_b32_e32 v226, 16, v11
	v_and_b32_e32 v227, 0xffff0000, v11
	v_mul_f32_e32 v220, v230, v220
	v_mul_f32_e32 v221, v230, v221
	v_mul_f32_e32 v222, v230, v222
	v_mul_f32_e32 v223, v230, v223
	v_mul_f32_e32 v224, v230, v224
	v_mul_f32_e32 v225, v230, v225
	v_mul_f32_e32 v226, v230, v226
	v_mul_f32_e32 v227, v230, v227
	v_fma_f32 v0, v229, v0, v220
	v_fma_f32 v1, v229, v1, v221
	v_fma_f32 v2, v229, v2, v222
	v_fma_f32 v3, v229, v3, v223
	v_fma_f32 v4, v229, v4, v224
	v_fma_f32 v5, v229, v5, v225
	v_fma_f32 v6, v229, v6, v226
	v_fma_f32 v7, v229, v7, v227
	s_add_i32 s13, s13, s10
	s_cmp_eq_u32 s13, s11
	s_cselect_b32 s13, s8, s13
	v_cvt_pk_bf16_f32 v216, v0, v1
	v_cvt_pk_bf16_f32 v217, v2, v3
	v_cvt_pk_bf16_f32 v218, v4, v5
	v_cvt_pk_bf16_f32 v219, v6, v7
	s_lshl_b32 s14, s13, 15
	s_add_u32 s16, s66, s14
	s_addc_u32 s17, s67, 0
	global_store_dwordx4 v236, v[216:219], s[16:17]
	v_readlane_b32 s18, v232, 1
	v_readlane_b32 s19, v233, 1
	s_nop 1
	v_add_f32_e32 v231, s18, v228
	v_max_f32_e32 v228, s19, v231
	v_sub_f32_e32 v231, v231, v228
	v_sub_f32_e32 v229, s19, v228
	v_mul_f32_e32 v231, 0x3fb8aa3b, v231
	v_mul_f32_e32 v229, 0x3fb8aa3b, v229
	v_exp_f32_e32 v230, v229
	v_exp_f32_e32 v229, v231
	s_nop 0
	v_lshlrev_b32_e32 v220, 16, v12
	v_and_b32_e32 v221, 0xffff0000, v12
	v_lshlrev_b32_e32 v222, 16, v13
	v_and_b32_e32 v223, 0xffff0000, v13
	v_lshlrev_b32_e32 v224, 16, v14
	v_and_b32_e32 v225, 0xffff0000, v14
	v_lshlrev_b32_e32 v226, 16, v15
	v_and_b32_e32 v227, 0xffff0000, v15
	v_mul_f32_e32 v220, v230, v220
	v_mul_f32_e32 v221, v230, v221
	v_mul_f32_e32 v222, v230, v222
	v_mul_f32_e32 v223, v230, v223
	v_mul_f32_e32 v224, v230, v224
	v_mul_f32_e32 v225, v230, v225
	v_mul_f32_e32 v226, v230, v226
	v_mul_f32_e32 v227, v230, v227
	v_fma_f32 v0, v229, v0, v220
	v_fma_f32 v1, v229, v1, v221
	v_fma_f32 v2, v229, v2, v222
	v_fma_f32 v3, v229, v3, v223
	v_fma_f32 v4, v229, v4, v224
	v_fma_f32 v5, v229, v5, v225
	v_fma_f32 v6, v229, v6, v226
	v_fma_f32 v7, v229, v7, v227
	s_add_i32 s13, s13, s10
	s_cmp_eq_u32 s13, s11
	s_cselect_b32 s13, s8, s13
	v_cvt_pk_bf16_f32 v216, v0, v1
	v_cvt_pk_bf16_f32 v217, v2, v3
	v_cvt_pk_bf16_f32 v218, v4, v5
	v_cvt_pk_bf16_f32 v219, v6, v7
	s_lshl_b32 s14, s13, 15
	s_add_u32 s16, s66, s14
	s_addc_u32 s17, s67, 0
	global_store_dwordx4 v236, v[216:219], s[16:17]
	v_readlane_b32 s18, v232, 2
	v_readlane_b32 s19, v233, 2
	s_nop 1
	v_add_f32_e32 v231, s18, v228
	v_max_f32_e32 v228, s19, v231
	v_sub_f32_e32 v231, v231, v228
	v_sub_f32_e32 v229, s19, v228
	v_mul_f32_e32 v231, 0x3fb8aa3b, v231
	v_mul_f32_e32 v229, 0x3fb8aa3b, v229
	v_exp_f32_e32 v230, v229
	v_exp_f32_e32 v229, v231
	s_nop 0
	v_lshlrev_b32_e32 v220, 16, v16
	v_and_b32_e32 v221, 0xffff0000, v16
	v_lshlrev_b32_e32 v222, 16, v17
	v_and_b32_e32 v223, 0xffff0000, v17
	v_lshlrev_b32_e32 v224, 16, v18
	v_and_b32_e32 v225, 0xffff0000, v18
	v_lshlrev_b32_e32 v226, 16, v19
	v_and_b32_e32 v227, 0xffff0000, v19
	v_mul_f32_e32 v220, v230, v220
	v_mul_f32_e32 v221, v230, v221
	v_mul_f32_e32 v222, v230, v222
	v_mul_f32_e32 v223, v230, v223
	v_mul_f32_e32 v224, v230, v224
	v_mul_f32_e32 v225, v230, v225
	v_mul_f32_e32 v226, v230, v226
	v_mul_f32_e32 v227, v230, v227
	v_fma_f32 v0, v229, v0, v220
	v_fma_f32 v1, v229, v1, v221
	v_fma_f32 v2, v229, v2, v222
	v_fma_f32 v3, v229, v3, v223
	v_fma_f32 v4, v229, v4, v224
	v_fma_f32 v5, v229, v5, v225
	v_fma_f32 v6, v229, v6, v226
	v_fma_f32 v7, v229, v7, v227
	s_add_i32 s13, s13, s10
	s_cmp_eq_u32 s13, s11
	s_cselect_b32 s13, s8, s13
	v_cvt_pk_bf16_f32 v216, v0, v1
	v_cvt_pk_bf16_f32 v217, v2, v3
	v_cvt_pk_bf16_f32 v218, v4, v5
	v_cvt_pk_bf16_f32 v219, v6, v7
	s_lshl_b32 s14, s13, 15
	s_add_u32 s16, s66, s14
	s_addc_u32 s17, s67, 0
	global_store_dwordx4 v236, v[216:219], s[16:17]
	v_readlane_b32 s18, v232, 3
	v_readlane_b32 s19, v233, 3
	s_nop 1
	v_add_f32_e32 v231, s18, v228
	v_max_f32_e32 v228, s19, v231
	v_sub_f32_e32 v231, v231, v228
	v_sub_f32_e32 v229, s19, v228
	v_mul_f32_e32 v231, 0x3fb8aa3b, v231
	v_mul_f32_e32 v229, 0x3fb8aa3b, v229
	v_exp_f32_e32 v230, v229
	v_exp_f32_e32 v229, v231
	s_nop 0
	v_lshlrev_b32_e32 v220, 16, v20
	v_and_b32_e32 v221, 0xffff0000, v20
	v_lshlrev_b32_e32 v222, 16, v21
	v_and_b32_e32 v223, 0xffff0000, v21
	v_lshlrev_b32_e32 v224, 16, v22
	v_and_b32_e32 v225, 0xffff0000, v22
	v_lshlrev_b32_e32 v226, 16, v23
	v_and_b32_e32 v227, 0xffff0000, v23
	v_mul_f32_e32 v220, v230, v220
	v_mul_f32_e32 v221, v230, v221
	v_mul_f32_e32 v222, v230, v222
	v_mul_f32_e32 v223, v230, v223
	v_mul_f32_e32 v224, v230, v224
	v_mul_f32_e32 v225, v230, v225
	v_mul_f32_e32 v226, v230, v226
	v_mul_f32_e32 v227, v230, v227
	v_fma_f32 v0, v229, v0, v220
	v_fma_f32 v1, v229, v1, v221
	v_fma_f32 v2, v229, v2, v222
	v_fma_f32 v3, v229, v3, v223
	v_fma_f32 v4, v229, v4, v224
	v_fma_f32 v5, v229, v5, v225
	v_fma_f32 v6, v229, v6, v226
	v_fma_f32 v7, v229, v7, v227
	s_add_i32 s13, s13, s10
	s_cmp_eq_u32 s13, s11
	s_cselect_b32 s13, s8, s13
	v_cvt_pk_bf16_f32 v216, v0, v1
	v_cvt_pk_bf16_f32 v217, v2, v3
	v_cvt_pk_bf16_f32 v218, v4, v5
	v_cvt_pk_bf16_f32 v219, v6, v7
	s_lshl_b32 s14, s13, 15
	s_add_u32 s16, s66, s14
	s_addc_u32 s17, s67, 0
	global_store_dwordx4 v236, v[216:219], s[16:17]
	v_readlane_b32 s18, v232, 4
	v_readlane_b32 s19, v233, 4
	s_nop 1
	v_add_f32_e32 v231, s18, v228
	v_max_f32_e32 v228, s19, v231
	v_sub_f32_e32 v231, v231, v228
	v_sub_f32_e32 v229, s19, v228
	v_mul_f32_e32 v231, 0x3fb8aa3b, v231
	v_mul_f32_e32 v229, 0x3fb8aa3b, v229
	v_exp_f32_e32 v230, v229
	v_exp_f32_e32 v229, v231
	s_nop 0
	v_lshlrev_b32_e32 v220, 16, v24
	v_and_b32_e32 v221, 0xffff0000, v24
	v_lshlrev_b32_e32 v222, 16, v25
	v_and_b32_e32 v223, 0xffff0000, v25
	v_lshlrev_b32_e32 v224, 16, v26
	v_and_b32_e32 v225, 0xffff0000, v26
	v_lshlrev_b32_e32 v226, 16, v27
	v_and_b32_e32 v227, 0xffff0000, v27
	v_mul_f32_e32 v220, v230, v220
	v_mul_f32_e32 v221, v230, v221
	v_mul_f32_e32 v222, v230, v222
	v_mul_f32_e32 v223, v230, v223
	v_mul_f32_e32 v224, v230, v224
	v_mul_f32_e32 v225, v230, v225
	v_mul_f32_e32 v226, v230, v226
	v_mul_f32_e32 v227, v230, v227
	v_fma_f32 v0, v229, v0, v220
	v_fma_f32 v1, v229, v1, v221
	v_fma_f32 v2, v229, v2, v222
	v_fma_f32 v3, v229, v3, v223
	v_fma_f32 v4, v229, v4, v224
	v_fma_f32 v5, v229, v5, v225
	v_fma_f32 v6, v229, v6, v226
	v_fma_f32 v7, v229, v7, v227
	s_add_i32 s13, s13, s10
	s_cmp_eq_u32 s13, s11
	s_cselect_b32 s13, s8, s13
	v_cvt_pk_bf16_f32 v216, v0, v1
	v_cvt_pk_bf16_f32 v217, v2, v3
	v_cvt_pk_bf16_f32 v218, v4, v5
	v_cvt_pk_bf16_f32 v219, v6, v7
	s_lshl_b32 s14, s13, 15
	s_add_u32 s16, s66, s14
	s_addc_u32 s17, s67, 0
	global_store_dwordx4 v236, v[216:219], s[16:17]
	v_readlane_b32 s18, v232, 5
	v_readlane_b32 s19, v233, 5
	s_nop 1
	v_add_f32_e32 v231, s18, v228
	v_max_f32_e32 v228, s19, v231
	v_sub_f32_e32 v231, v231, v228
	v_sub_f32_e32 v229, s19, v228
	v_mul_f32_e32 v231, 0x3fb8aa3b, v231
	v_mul_f32_e32 v229, 0x3fb8aa3b, v229
	v_exp_f32_e32 v230, v229
	v_exp_f32_e32 v229, v231
	s_nop 0
	v_lshlrev_b32_e32 v220, 16, v28
	v_and_b32_e32 v221, 0xffff0000, v28
	v_lshlrev_b32_e32 v222, 16, v29
	v_and_b32_e32 v223, 0xffff0000, v29
	v_lshlrev_b32_e32 v224, 16, v30
	v_and_b32_e32 v225, 0xffff0000, v30
	v_lshlrev_b32_e32 v226, 16, v31
	v_and_b32_e32 v227, 0xffff0000, v31
	v_mul_f32_e32 v220, v230, v220
	v_mul_f32_e32 v221, v230, v221
	v_mul_f32_e32 v222, v230, v222
	v_mul_f32_e32 v223, v230, v223
	v_mul_f32_e32 v224, v230, v224
	v_mul_f32_e32 v225, v230, v225
	v_mul_f32_e32 v226, v230, v226
	v_mul_f32_e32 v227, v230, v227
	v_fma_f32 v0, v229, v0, v220
	v_fma_f32 v1, v229, v1, v221
	v_fma_f32 v2, v229, v2, v222
	v_fma_f32 v3, v229, v3, v223
	v_fma_f32 v4, v229, v4, v224
	v_fma_f32 v5, v229, v5, v225
	v_fma_f32 v6, v229, v6, v226
	v_fma_f32 v7, v229, v7, v227
	s_add_i32 s13, s13, s10
	s_cmp_eq_u32 s13, s11
	s_cselect_b32 s13, s8, s13
	v_cvt_pk_bf16_f32 v216, v0, v1
	v_cvt_pk_bf16_f32 v217, v2, v3
	v_cvt_pk_bf16_f32 v218, v4, v5
	v_cvt_pk_bf16_f32 v219, v6, v7
	s_lshl_b32 s14, s13, 15
	s_add_u32 s16, s66, s14
	s_addc_u32 s17, s67, 0
	global_store_dwordx4 v236, v[216:219], s[16:17]
	v_readlane_b32 s18, v232, 6
	v_readlane_b32 s19, v233, 6
	s_nop 1
	v_add_f32_e32 v231, s18, v228
	v_max_f32_e32 v228, s19, v231
	v_sub_f32_e32 v231, v231, v228
	v_sub_f32_e32 v229, s19, v228
	v_mul_f32_e32 v231, 0x3fb8aa3b, v231
	v_mul_f32_e32 v229, 0x3fb8aa3b, v229
	v_exp_f32_e32 v230, v229
	v_exp_f32_e32 v229, v231
	s_nop 0
	v_lshlrev_b32_e32 v220, 16, v32
	v_and_b32_e32 v221, 0xffff0000, v32
	v_lshlrev_b32_e32 v222, 16, v33
	v_and_b32_e32 v223, 0xffff0000, v33
	v_lshlrev_b32_e32 v224, 16, v34
	v_and_b32_e32 v225, 0xffff0000, v34
	v_lshlrev_b32_e32 v226, 16, v35
	v_and_b32_e32 v227, 0xffff0000, v35
	v_mul_f32_e32 v220, v230, v220
	v_mul_f32_e32 v221, v230, v221
	v_mul_f32_e32 v222, v230, v222
	v_mul_f32_e32 v223, v230, v223
	v_mul_f32_e32 v224, v230, v224
	v_mul_f32_e32 v225, v230, v225
	v_mul_f32_e32 v226, v230, v226
	v_mul_f32_e32 v227, v230, v227
	v_fma_f32 v0, v229, v0, v220
	v_fma_f32 v1, v229, v1, v221
	v_fma_f32 v2, v229, v2, v222
	v_fma_f32 v3, v229, v3, v223
	v_fma_f32 v4, v229, v4, v224
	v_fma_f32 v5, v229, v5, v225
	v_fma_f32 v6, v229, v6, v226
	v_fma_f32 v7, v229, v7, v227
	s_add_i32 s13, s13, s10
	s_cmp_eq_u32 s13, s11
	s_cselect_b32 s13, s8, s13
	v_cvt_pk_bf16_f32 v216, v0, v1
	v_cvt_pk_bf16_f32 v217, v2, v3
	v_cvt_pk_bf16_f32 v218, v4, v5
	v_cvt_pk_bf16_f32 v219, v6, v7
	s_lshl_b32 s14, s13, 15
	s_add_u32 s16, s66, s14
	s_addc_u32 s17, s67, 0
	global_store_dwordx4 v236, v[216:219], s[16:17]
	v_readlane_b32 s18, v232, 7
	v_readlane_b32 s19, v233, 7
	s_nop 1
	v_add_f32_e32 v231, s18, v228
	v_max_f32_e32 v228, s19, v231
	v_sub_f32_e32 v231, v231, v228
	v_sub_f32_e32 v229, s19, v228
	v_mul_f32_e32 v231, 0x3fb8aa3b, v231
	v_mul_f32_e32 v229, 0x3fb8aa3b, v229
	v_exp_f32_e32 v230, v229
	v_exp_f32_e32 v229, v231
	s_nop 0
	v_lshlrev_b32_e32 v220, 16, v36
	v_and_b32_e32 v221, 0xffff0000, v36
	v_lshlrev_b32_e32 v222, 16, v37
	v_and_b32_e32 v223, 0xffff0000, v37
	v_lshlrev_b32_e32 v224, 16, v38
	v_and_b32_e32 v225, 0xffff0000, v38
	v_lshlrev_b32_e32 v226, 16, v39
	v_and_b32_e32 v227, 0xffff0000, v39
	v_mul_f32_e32 v220, v230, v220
	v_mul_f32_e32 v221, v230, v221
	v_mul_f32_e32 v222, v230, v222
	v_mul_f32_e32 v223, v230, v223
	v_mul_f32_e32 v224, v230, v224
	v_mul_f32_e32 v225, v230, v225
	v_mul_f32_e32 v226, v230, v226
	v_mul_f32_e32 v227, v230, v227
	v_fma_f32 v0, v229, v0, v220
	v_fma_f32 v1, v229, v1, v221
	v_fma_f32 v2, v229, v2, v222
	v_fma_f32 v3, v229, v3, v223
	v_fma_f32 v4, v229, v4, v224
	v_fma_f32 v5, v229, v5, v225
	v_fma_f32 v6, v229, v6, v226
	v_fma_f32 v7, v229, v7, v227
	s_add_i32 s13, s13, s10
	s_cmp_eq_u32 s13, s11
	s_cselect_b32 s13, s8, s13
	v_cvt_pk_bf16_f32 v216, v0, v1
	v_cvt_pk_bf16_f32 v217, v2, v3
	v_cvt_pk_bf16_f32 v218, v4, v5
	v_cvt_pk_bf16_f32 v219, v6, v7
	s_lshl_b32 s14, s13, 15
	s_add_u32 s16, s66, s14
	s_addc_u32 s17, s67, 0
	global_store_dwordx4 v236, v[216:219], s[16:17]
	v_readlane_b32 s18, v232, 8
	v_readlane_b32 s19, v233, 8
	s_nop 1
	v_add_f32_e32 v231, s18, v228
	v_max_f32_e32 v228, s19, v231
	v_sub_f32_e32 v231, v231, v228
	v_sub_f32_e32 v229, s19, v228
	v_mul_f32_e32 v231, 0x3fb8aa3b, v231
	v_mul_f32_e32 v229, 0x3fb8aa3b, v229
	v_exp_f32_e32 v230, v229
	v_exp_f32_e32 v229, v231
	s_nop 0
	v_lshlrev_b32_e32 v220, 16, v40
	v_and_b32_e32 v221, 0xffff0000, v40
	v_lshlrev_b32_e32 v222, 16, v41
	v_and_b32_e32 v223, 0xffff0000, v41
	v_lshlrev_b32_e32 v224, 16, v42
	v_and_b32_e32 v225, 0xffff0000, v42
	v_lshlrev_b32_e32 v226, 16, v43
	v_and_b32_e32 v227, 0xffff0000, v43
	v_mul_f32_e32 v220, v230, v220
	v_mul_f32_e32 v221, v230, v221
	v_mul_f32_e32 v222, v230, v222
	v_mul_f32_e32 v223, v230, v223
	v_mul_f32_e32 v224, v230, v224
	v_mul_f32_e32 v225, v230, v225
	v_mul_f32_e32 v226, v230, v226
	v_mul_f32_e32 v227, v230, v227
	v_fma_f32 v0, v229, v0, v220
	v_fma_f32 v1, v229, v1, v221
	v_fma_f32 v2, v229, v2, v222
	v_fma_f32 v3, v229, v3, v223
	v_fma_f32 v4, v229, v4, v224
	v_fma_f32 v5, v229, v5, v225
	v_fma_f32 v6, v229, v6, v226
	v_fma_f32 v7, v229, v7, v227
	s_add_i32 s13, s13, s10
	s_cmp_eq_u32 s13, s11
	s_cselect_b32 s13, s8, s13
	v_cvt_pk_bf16_f32 v216, v0, v1
	v_cvt_pk_bf16_f32 v217, v2, v3
	v_cvt_pk_bf16_f32 v218, v4, v5
	v_cvt_pk_bf16_f32 v219, v6, v7
	s_lshl_b32 s14, s13, 15
	s_add_u32 s16, s66, s14
	s_addc_u32 s17, s67, 0
	global_store_dwordx4 v236, v[216:219], s[16:17]
	v_readlane_b32 s18, v232, 9
	v_readlane_b32 s19, v233, 9
	s_nop 1
	v_add_f32_e32 v231, s18, v228
	v_max_f32_e32 v228, s19, v231
	v_sub_f32_e32 v231, v231, v228
	v_sub_f32_e32 v229, s19, v228
	v_mul_f32_e32 v231, 0x3fb8aa3b, v231
	v_mul_f32_e32 v229, 0x3fb8aa3b, v229
	v_exp_f32_e32 v230, v229
	v_exp_f32_e32 v229, v231
	s_nop 0
	v_lshlrev_b32_e32 v220, 16, v44
	v_and_b32_e32 v221, 0xffff0000, v44
	v_lshlrev_b32_e32 v222, 16, v45
	v_and_b32_e32 v223, 0xffff0000, v45
	v_lshlrev_b32_e32 v224, 16, v46
	v_and_b32_e32 v225, 0xffff0000, v46
	v_lshlrev_b32_e32 v226, 16, v47
	v_and_b32_e32 v227, 0xffff0000, v47
	v_mul_f32_e32 v220, v230, v220
	v_mul_f32_e32 v221, v230, v221
	v_mul_f32_e32 v222, v230, v222
	v_mul_f32_e32 v223, v230, v223
	v_mul_f32_e32 v224, v230, v224
	v_mul_f32_e32 v225, v230, v225
	v_mul_f32_e32 v226, v230, v226
	v_mul_f32_e32 v227, v230, v227
	v_fma_f32 v0, v229, v0, v220
	v_fma_f32 v1, v229, v1, v221
	v_fma_f32 v2, v229, v2, v222
	v_fma_f32 v3, v229, v3, v223
	v_fma_f32 v4, v229, v4, v224
	v_fma_f32 v5, v229, v5, v225
	v_fma_f32 v6, v229, v6, v226
	v_fma_f32 v7, v229, v7, v227
	s_add_i32 s13, s13, s10
	s_cmp_eq_u32 s13, s11
	s_cselect_b32 s13, s8, s13
	v_cvt_pk_bf16_f32 v216, v0, v1
	v_cvt_pk_bf16_f32 v217, v2, v3
	v_cvt_pk_bf16_f32 v218, v4, v5
	v_cvt_pk_bf16_f32 v219, v6, v7
	s_lshl_b32 s14, s13, 15
	s_add_u32 s16, s66, s14
	s_addc_u32 s17, s67, 0
	global_store_dwordx4 v236, v[216:219], s[16:17]
	v_readlane_b32 s18, v232, 10
	v_readlane_b32 s19, v233, 10
	s_nop 1
	v_add_f32_e32 v231, s18, v228
	v_max_f32_e32 v228, s19, v231
	v_sub_f32_e32 v231, v231, v228
	v_sub_f32_e32 v229, s19, v228
	v_mul_f32_e32 v231, 0x3fb8aa3b, v231
	v_mul_f32_e32 v229, 0x3fb8aa3b, v229
	v_exp_f32_e32 v230, v229
	v_exp_f32_e32 v229, v231
	s_nop 0
	v_lshlrev_b32_e32 v220, 16, v48
	v_and_b32_e32 v221, 0xffff0000, v48
	v_lshlrev_b32_e32 v222, 16, v49
	v_and_b32_e32 v223, 0xffff0000, v49
	v_lshlrev_b32_e32 v224, 16, v50
	v_and_b32_e32 v225, 0xffff0000, v50
	v_lshlrev_b32_e32 v226, 16, v51
	v_and_b32_e32 v227, 0xffff0000, v51
	v_mul_f32_e32 v220, v230, v220
	v_mul_f32_e32 v221, v230, v221
	v_mul_f32_e32 v222, v230, v222
	v_mul_f32_e32 v223, v230, v223
	v_mul_f32_e32 v224, v230, v224
	v_mul_f32_e32 v225, v230, v225
	v_mul_f32_e32 v226, v230, v226
	v_mul_f32_e32 v227, v230, v227
	v_fma_f32 v0, v229, v0, v220
	v_fma_f32 v1, v229, v1, v221
	v_fma_f32 v2, v229, v2, v222
	v_fma_f32 v3, v229, v3, v223
	v_fma_f32 v4, v229, v4, v224
	v_fma_f32 v5, v229, v5, v225
	v_fma_f32 v6, v229, v6, v226
	v_fma_f32 v7, v229, v7, v227
	s_add_i32 s13, s13, s10
	s_cmp_eq_u32 s13, s11
	s_cselect_b32 s13, s8, s13
	v_cvt_pk_bf16_f32 v216, v0, v1
	v_cvt_pk_bf16_f32 v217, v2, v3
	v_cvt_pk_bf16_f32 v218, v4, v5
	v_cvt_pk_bf16_f32 v219, v6, v7
	s_lshl_b32 s14, s13, 15
	s_add_u32 s16, s66, s14
	s_addc_u32 s17, s67, 0
	global_store_dwordx4 v236, v[216:219], s[16:17]
	v_readlane_b32 s18, v232, 11
	v_readlane_b32 s19, v233, 11
	s_nop 1
	v_add_f32_e32 v231, s18, v228
	v_max_f32_e32 v228, s19, v231
	v_sub_f32_e32 v231, v231, v228
	v_sub_f32_e32 v229, s19, v228
	v_mul_f32_e32 v231, 0x3fb8aa3b, v231
	v_mul_f32_e32 v229, 0x3fb8aa3b, v229
	v_exp_f32_e32 v230, v229
	v_exp_f32_e32 v229, v231
	s_nop 0
	v_lshlrev_b32_e32 v220, 16, v52
	v_and_b32_e32 v221, 0xffff0000, v52
	v_lshlrev_b32_e32 v222, 16, v53
	v_and_b32_e32 v223, 0xffff0000, v53
	v_lshlrev_b32_e32 v224, 16, v54
	v_and_b32_e32 v225, 0xffff0000, v54
	v_lshlrev_b32_e32 v226, 16, v55
	v_and_b32_e32 v227, 0xffff0000, v55
	v_mul_f32_e32 v220, v230, v220
	v_mul_f32_e32 v221, v230, v221
	v_mul_f32_e32 v222, v230, v222
	v_mul_f32_e32 v223, v230, v223
	v_mul_f32_e32 v224, v230, v224
	v_mul_f32_e32 v225, v230, v225
	v_mul_f32_e32 v226, v230, v226
	v_mul_f32_e32 v227, v230, v227
	v_fma_f32 v0, v229, v0, v220
	v_fma_f32 v1, v229, v1, v221
	v_fma_f32 v2, v229, v2, v222
	v_fma_f32 v3, v229, v3, v223
	v_fma_f32 v4, v229, v4, v224
	v_fma_f32 v5, v229, v5, v225
	v_fma_f32 v6, v229, v6, v226
	v_fma_f32 v7, v229, v7, v227
	s_add_i32 s13, s13, s10
	s_cmp_eq_u32 s13, s11
	s_cselect_b32 s13, s8, s13
	v_cvt_pk_bf16_f32 v216, v0, v1
	v_cvt_pk_bf16_f32 v217, v2, v3
	v_cvt_pk_bf16_f32 v218, v4, v5
	v_cvt_pk_bf16_f32 v219, v6, v7
	s_lshl_b32 s14, s13, 15
	s_add_u32 s16, s66, s14
	s_addc_u32 s17, s67, 0
	global_store_dwordx4 v236, v[216:219], s[16:17]
	v_readlane_b32 s18, v232, 12
	v_readlane_b32 s19, v233, 12
	s_nop 1
	v_add_f32_e32 v231, s18, v228
	v_max_f32_e32 v228, s19, v231
	v_sub_f32_e32 v231, v231, v228
	v_sub_f32_e32 v229, s19, v228
	v_mul_f32_e32 v231, 0x3fb8aa3b, v231
	v_mul_f32_e32 v229, 0x3fb8aa3b, v229
	v_exp_f32_e32 v230, v229
	v_exp_f32_e32 v229, v231
	s_nop 0
	v_lshlrev_b32_e32 v220, 16, v56
	v_and_b32_e32 v221, 0xffff0000, v56
	v_lshlrev_b32_e32 v222, 16, v57
	v_and_b32_e32 v223, 0xffff0000, v57
	v_lshlrev_b32_e32 v224, 16, v58
	v_and_b32_e32 v225, 0xffff0000, v58
	v_lshlrev_b32_e32 v226, 16, v59
	v_and_b32_e32 v227, 0xffff0000, v59
	v_mul_f32_e32 v220, v230, v220
	v_mul_f32_e32 v221, v230, v221
	v_mul_f32_e32 v222, v230, v222
	v_mul_f32_e32 v223, v230, v223
	v_mul_f32_e32 v224, v230, v224
	v_mul_f32_e32 v225, v230, v225
	v_mul_f32_e32 v226, v230, v226
	v_mul_f32_e32 v227, v230, v227
	v_fma_f32 v0, v229, v0, v220
	v_fma_f32 v1, v229, v1, v221
	v_fma_f32 v2, v229, v2, v222
	v_fma_f32 v3, v229, v3, v223
	v_fma_f32 v4, v229, v4, v224
	v_fma_f32 v5, v229, v5, v225
	v_fma_f32 v6, v229, v6, v226
	v_fma_f32 v7, v229, v7, v227
	s_add_i32 s13, s13, s10
	s_cmp_eq_u32 s13, s11
	s_cselect_b32 s13, s8, s13
	v_cvt_pk_bf16_f32 v216, v0, v1
	v_cvt_pk_bf16_f32 v217, v2, v3
	v_cvt_pk_bf16_f32 v218, v4, v5
	v_cvt_pk_bf16_f32 v219, v6, v7
	s_lshl_b32 s14, s13, 15
	s_add_u32 s16, s66, s14
	s_addc_u32 s17, s67, 0
	global_store_dwordx4 v236, v[216:219], s[16:17]
	v_readlane_b32 s18, v232, 13
	v_readlane_b32 s19, v233, 13
	s_nop 1
	v_add_f32_e32 v231, s18, v228
	v_max_f32_e32 v228, s19, v231
	v_sub_f32_e32 v231, v231, v228
	v_sub_f32_e32 v229, s19, v228
	v_mul_f32_e32 v231, 0x3fb8aa3b, v231
	v_mul_f32_e32 v229, 0x3fb8aa3b, v229
	v_exp_f32_e32 v230, v229
	v_exp_f32_e32 v229, v231
	s_nop 0
	v_lshlrev_b32_e32 v220, 16, v60
	v_and_b32_e32 v221, 0xffff0000, v60
	v_lshlrev_b32_e32 v222, 16, v61
	v_and_b32_e32 v223, 0xffff0000, v61
	v_lshlrev_b32_e32 v224, 16, v62
	v_and_b32_e32 v225, 0xffff0000, v62
	v_lshlrev_b32_e32 v226, 16, v63
	v_and_b32_e32 v227, 0xffff0000, v63
	v_mul_f32_e32 v220, v230, v220
	v_mul_f32_e32 v221, v230, v221
	v_mul_f32_e32 v222, v230, v222
	v_mul_f32_e32 v223, v230, v223
	v_mul_f32_e32 v224, v230, v224
	v_mul_f32_e32 v225, v230, v225
	v_mul_f32_e32 v226, v230, v226
	v_mul_f32_e32 v227, v230, v227
	v_fma_f32 v0, v229, v0, v220
	v_fma_f32 v1, v229, v1, v221
	v_fma_f32 v2, v229, v2, v222
	v_fma_f32 v3, v229, v3, v223
	v_fma_f32 v4, v229, v4, v224
	v_fma_f32 v5, v229, v5, v225
	v_fma_f32 v6, v229, v6, v226
	v_fma_f32 v7, v229, v7, v227
	s_add_i32 s13, s13, s10
	s_cmp_eq_u32 s13, s11
	s_cselect_b32 s13, s8, s13
	v_cvt_pk_bf16_f32 v216, v0, v1
	v_cvt_pk_bf16_f32 v217, v2, v3
	v_cvt_pk_bf16_f32 v218, v4, v5
	v_cvt_pk_bf16_f32 v219, v6, v7
	s_lshl_b32 s14, s13, 15
	s_add_u32 s16, s66, s14
	s_addc_u32 s17, s67, 0
	global_store_dwordx4 v236, v[216:219], s[16:17]
	v_readlane_b32 s18, v232, 14
	v_readlane_b32 s19, v233, 14
	s_nop 1
	v_add_f32_e32 v231, s18, v228
	v_max_f32_e32 v228, s19, v231
	v_sub_f32_e32 v231, v231, v228
	v_sub_f32_e32 v229, s19, v228
	v_mul_f32_e32 v231, 0x3fb8aa3b, v231
	v_mul_f32_e32 v229, 0x3fb8aa3b, v229
	v_exp_f32_e32 v230, v229
	v_exp_f32_e32 v229, v231
	s_nop 0
	v_lshlrev_b32_e32 v220, 16, v64
	v_and_b32_e32 v221, 0xffff0000, v64
	v_lshlrev_b32_e32 v222, 16, v65
	v_and_b32_e32 v223, 0xffff0000, v65
	v_lshlrev_b32_e32 v224, 16, v66
	v_and_b32_e32 v225, 0xffff0000, v66
	v_lshlrev_b32_e32 v226, 16, v67
	v_and_b32_e32 v227, 0xffff0000, v67
	v_mul_f32_e32 v220, v230, v220
	v_mul_f32_e32 v221, v230, v221
	v_mul_f32_e32 v222, v230, v222
	v_mul_f32_e32 v223, v230, v223
	v_mul_f32_e32 v224, v230, v224
	v_mul_f32_e32 v225, v230, v225
	v_mul_f32_e32 v226, v230, v226
	v_mul_f32_e32 v227, v230, v227
	v_fma_f32 v0, v229, v0, v220
	v_fma_f32 v1, v229, v1, v221
	v_fma_f32 v2, v229, v2, v222
	v_fma_f32 v3, v229, v3, v223
	v_fma_f32 v4, v229, v4, v224
	v_fma_f32 v5, v229, v5, v225
	v_fma_f32 v6, v229, v6, v226
	v_fma_f32 v7, v229, v7, v227
	s_add_i32 s13, s13, s10
	s_cmp_eq_u32 s13, s11
	s_cselect_b32 s13, s8, s13
	v_cvt_pk_bf16_f32 v216, v0, v1
	v_cvt_pk_bf16_f32 v217, v2, v3
	v_cvt_pk_bf16_f32 v218, v4, v5
	v_cvt_pk_bf16_f32 v219, v6, v7
	s_lshl_b32 s14, s13, 15
	s_add_u32 s16, s66, s14
	s_addc_u32 s17, s67, 0
	global_store_dwordx4 v236, v[216:219], s[16:17]
	v_readlane_b32 s18, v232, 15
	v_readlane_b32 s19, v233, 15
	s_nop 1
	v_add_f32_e32 v231, s18, v228
	v_max_f32_e32 v228, s19, v231
	v_sub_f32_e32 v231, v231, v228
	v_sub_f32_e32 v229, s19, v228
	v_mul_f32_e32 v231, 0x3fb8aa3b, v231
	v_mul_f32_e32 v229, 0x3fb8aa3b, v229
	v_exp_f32_e32 v230, v229
	v_exp_f32_e32 v229, v231
	s_nop 0
	v_lshlrev_b32_e32 v220, 16, v68
	v_and_b32_e32 v221, 0xffff0000, v68
	v_lshlrev_b32_e32 v222, 16, v69
	v_and_b32_e32 v223, 0xffff0000, v69
	v_lshlrev_b32_e32 v224, 16, v70
	v_and_b32_e32 v225, 0xffff0000, v70
	v_lshlrev_b32_e32 v226, 16, v71
	v_and_b32_e32 v227, 0xffff0000, v71
	v_mul_f32_e32 v220, v230, v220
	v_mul_f32_e32 v221, v230, v221
	v_mul_f32_e32 v222, v230, v222
	v_mul_f32_e32 v223, v230, v223
	v_mul_f32_e32 v224, v230, v224
	v_mul_f32_e32 v225, v230, v225
	v_mul_f32_e32 v226, v230, v226
	v_mul_f32_e32 v227, v230, v227
	v_fma_f32 v0, v229, v0, v220
	v_fma_f32 v1, v229, v1, v221
	v_fma_f32 v2, v229, v2, v222
	v_fma_f32 v3, v229, v3, v223
	v_fma_f32 v4, v229, v4, v224
	v_fma_f32 v5, v229, v5, v225
	v_fma_f32 v6, v229, v6, v226
	v_fma_f32 v7, v229, v7, v227
	s_add_i32 s13, s13, s10
	s_cmp_eq_u32 s13, s11
	s_cselect_b32 s13, s8, s13
	v_cvt_pk_bf16_f32 v216, v0, v1
	v_cvt_pk_bf16_f32 v217, v2, v3
	v_cvt_pk_bf16_f32 v218, v4, v5
	v_cvt_pk_bf16_f32 v219, v6, v7
	s_lshl_b32 s14, s13, 15
	s_add_u32 s16, s66, s14
	s_addc_u32 s17, s67, 0
	global_store_dwordx4 v236, v[216:219], s[16:17]
	v_readlane_b32 s18, v232, 16
	v_readlane_b32 s19, v233, 16
	s_nop 1
	v_add_f32_e32 v231, s18, v228
	v_max_f32_e32 v228, s19, v231
	v_sub_f32_e32 v231, v231, v228
	v_sub_f32_e32 v229, s19, v228
	v_mul_f32_e32 v231, 0x3fb8aa3b, v231
	v_mul_f32_e32 v229, 0x3fb8aa3b, v229
	v_exp_f32_e32 v230, v229
	v_exp_f32_e32 v229, v231
	s_nop 0
	v_lshlrev_b32_e32 v220, 16, v72
	v_and_b32_e32 v221, 0xffff0000, v72
	v_lshlrev_b32_e32 v222, 16, v73
	v_and_b32_e32 v223, 0xffff0000, v73
	v_lshlrev_b32_e32 v224, 16, v74
	v_and_b32_e32 v225, 0xffff0000, v74
	v_lshlrev_b32_e32 v226, 16, v75
	v_and_b32_e32 v227, 0xffff0000, v75
	v_mul_f32_e32 v220, v230, v220
	v_mul_f32_e32 v221, v230, v221
	v_mul_f32_e32 v222, v230, v222
	v_mul_f32_e32 v223, v230, v223
	v_mul_f32_e32 v224, v230, v224
	v_mul_f32_e32 v225, v230, v225
	v_mul_f32_e32 v226, v230, v226
	v_mul_f32_e32 v227, v230, v227
	v_fma_f32 v0, v229, v0, v220
	v_fma_f32 v1, v229, v1, v221
	v_fma_f32 v2, v229, v2, v222
	v_fma_f32 v3, v229, v3, v223
	v_fma_f32 v4, v229, v4, v224
	v_fma_f32 v5, v229, v5, v225
	v_fma_f32 v6, v229, v6, v226
	v_fma_f32 v7, v229, v7, v227
	s_add_i32 s13, s13, s10
	s_cmp_eq_u32 s13, s11
	s_cselect_b32 s13, s8, s13
	v_cvt_pk_bf16_f32 v216, v0, v1
	v_cvt_pk_bf16_f32 v217, v2, v3
	v_cvt_pk_bf16_f32 v218, v4, v5
	v_cvt_pk_bf16_f32 v219, v6, v7
	s_lshl_b32 s14, s13, 15
	s_add_u32 s16, s66, s14
	s_addc_u32 s17, s67, 0
	global_store_dwordx4 v236, v[216:219], s[16:17]
	v_readlane_b32 s18, v232, 17
	v_readlane_b32 s19, v233, 17
	s_nop 1
	v_add_f32_e32 v231, s18, v228
	v_max_f32_e32 v228, s19, v231
	v_sub_f32_e32 v231, v231, v228
	v_sub_f32_e32 v229, s19, v228
	v_mul_f32_e32 v231, 0x3fb8aa3b, v231
	v_mul_f32_e32 v229, 0x3fb8aa3b, v229
	v_exp_f32_e32 v230, v229
	v_exp_f32_e32 v229, v231
	s_nop 0
	v_lshlrev_b32_e32 v220, 16, v76
	v_and_b32_e32 v221, 0xffff0000, v76
	v_lshlrev_b32_e32 v222, 16, v77
	v_and_b32_e32 v223, 0xffff0000, v77
	v_lshlrev_b32_e32 v224, 16, v78
	v_and_b32_e32 v225, 0xffff0000, v78
	v_lshlrev_b32_e32 v226, 16, v79
	v_and_b32_e32 v227, 0xffff0000, v79
	v_mul_f32_e32 v220, v230, v220
	v_mul_f32_e32 v221, v230, v221
	v_mul_f32_e32 v222, v230, v222
	v_mul_f32_e32 v223, v230, v223
	v_mul_f32_e32 v224, v230, v224
	v_mul_f32_e32 v225, v230, v225
	v_mul_f32_e32 v226, v230, v226
	v_mul_f32_e32 v227, v230, v227
	v_fma_f32 v0, v229, v0, v220
	v_fma_f32 v1, v229, v1, v221
	v_fma_f32 v2, v229, v2, v222
	v_fma_f32 v3, v229, v3, v223
	v_fma_f32 v4, v229, v4, v224
	v_fma_f32 v5, v229, v5, v225
	v_fma_f32 v6, v229, v6, v226
	v_fma_f32 v7, v229, v7, v227
	s_add_i32 s13, s13, s10
	s_cmp_eq_u32 s13, s11
	s_cselect_b32 s13, s8, s13
	v_cvt_pk_bf16_f32 v216, v0, v1
	v_cvt_pk_bf16_f32 v217, v2, v3
	v_cvt_pk_bf16_f32 v218, v4, v5
	v_cvt_pk_bf16_f32 v219, v6, v7
	s_lshl_b32 s14, s13, 15
	s_add_u32 s16, s66, s14
	s_addc_u32 s17, s67, 0
	global_store_dwordx4 v236, v[216:219], s[16:17]
	v_readlane_b32 s18, v232, 18
	v_readlane_b32 s19, v233, 18
	s_nop 1
	v_add_f32_e32 v231, s18, v228
	v_max_f32_e32 v228, s19, v231
	v_sub_f32_e32 v231, v231, v228
	v_sub_f32_e32 v229, s19, v228
	v_mul_f32_e32 v231, 0x3fb8aa3b, v231
	v_mul_f32_e32 v229, 0x3fb8aa3b, v229
	v_exp_f32_e32 v230, v229
	v_exp_f32_e32 v229, v231
	s_nop 0
	v_lshlrev_b32_e32 v220, 16, v80
	v_and_b32_e32 v221, 0xffff0000, v80
	v_lshlrev_b32_e32 v222, 16, v81
	v_and_b32_e32 v223, 0xffff0000, v81
	v_lshlrev_b32_e32 v224, 16, v82
	v_and_b32_e32 v225, 0xffff0000, v82
	v_lshlrev_b32_e32 v226, 16, v83
	v_and_b32_e32 v227, 0xffff0000, v83
	v_mul_f32_e32 v220, v230, v220
	v_mul_f32_e32 v221, v230, v221
	v_mul_f32_e32 v222, v230, v222
	v_mul_f32_e32 v223, v230, v223
	v_mul_f32_e32 v224, v230, v224
	v_mul_f32_e32 v225, v230, v225
	v_mul_f32_e32 v226, v230, v226
	v_mul_f32_e32 v227, v230, v227
	v_fma_f32 v0, v229, v0, v220
	v_fma_f32 v1, v229, v1, v221
	v_fma_f32 v2, v229, v2, v222
	v_fma_f32 v3, v229, v3, v223
	v_fma_f32 v4, v229, v4, v224
	v_fma_f32 v5, v229, v5, v225
	v_fma_f32 v6, v229, v6, v226
	v_fma_f32 v7, v229, v7, v227
	s_add_i32 s13, s13, s10
	s_cmp_eq_u32 s13, s11
	s_cselect_b32 s13, s8, s13
	v_cvt_pk_bf16_f32 v216, v0, v1
	v_cvt_pk_bf16_f32 v217, v2, v3
	v_cvt_pk_bf16_f32 v218, v4, v5
	v_cvt_pk_bf16_f32 v219, v6, v7
	s_lshl_b32 s14, s13, 15
	s_add_u32 s16, s66, s14
	s_addc_u32 s17, s67, 0
	global_store_dwordx4 v236, v[216:219], s[16:17]
	v_readlane_b32 s18, v232, 19
	v_readlane_b32 s19, v233, 19
	s_nop 1
	v_add_f32_e32 v231, s18, v228
	v_max_f32_e32 v228, s19, v231
	v_sub_f32_e32 v231, v231, v228
	v_sub_f32_e32 v229, s19, v228
	v_mul_f32_e32 v231, 0x3fb8aa3b, v231
	v_mul_f32_e32 v229, 0x3fb8aa3b, v229
	v_exp_f32_e32 v230, v229
	v_exp_f32_e32 v229, v231
	s_nop 0
	v_lshlrev_b32_e32 v220, 16, v84
	v_and_b32_e32 v221, 0xffff0000, v84
	v_lshlrev_b32_e32 v222, 16, v85
	v_and_b32_e32 v223, 0xffff0000, v85
	v_lshlrev_b32_e32 v224, 16, v86
	v_and_b32_e32 v225, 0xffff0000, v86
	v_lshlrev_b32_e32 v226, 16, v87
	v_and_b32_e32 v227, 0xffff0000, v87
	v_mul_f32_e32 v220, v230, v220
	v_mul_f32_e32 v221, v230, v221
	v_mul_f32_e32 v222, v230, v222
	v_mul_f32_e32 v223, v230, v223
	v_mul_f32_e32 v224, v230, v224
	v_mul_f32_e32 v225, v230, v225
	v_mul_f32_e32 v226, v230, v226
	v_mul_f32_e32 v227, v230, v227
	v_fma_f32 v0, v229, v0, v220
	v_fma_f32 v1, v229, v1, v221
	v_fma_f32 v2, v229, v2, v222
	v_fma_f32 v3, v229, v3, v223
	v_fma_f32 v4, v229, v4, v224
	v_fma_f32 v5, v229, v5, v225
	v_fma_f32 v6, v229, v6, v226
	v_fma_f32 v7, v229, v7, v227
	s_add_i32 s13, s13, s10
	s_cmp_eq_u32 s13, s11
	s_cselect_b32 s13, s8, s13
	v_cvt_pk_bf16_f32 v216, v0, v1
	v_cvt_pk_bf16_f32 v217, v2, v3
	v_cvt_pk_bf16_f32 v218, v4, v5
	v_cvt_pk_bf16_f32 v219, v6, v7
	s_lshl_b32 s14, s13, 15
	s_add_u32 s16, s66, s14
	s_addc_u32 s17, s67, 0
	global_store_dwordx4 v236, v[216:219], s[16:17]
	v_readlane_b32 s18, v232, 20
	v_readlane_b32 s19, v233, 20
	s_nop 1
	v_add_f32_e32 v231, s18, v228
	v_max_f32_e32 v228, s19, v231
	v_sub_f32_e32 v231, v231, v228
	v_sub_f32_e32 v229, s19, v228
	v_mul_f32_e32 v231, 0x3fb8aa3b, v231
	v_mul_f32_e32 v229, 0x3fb8aa3b, v229
	v_exp_f32_e32 v230, v229
	v_exp_f32_e32 v229, v231
	s_nop 0
	v_lshlrev_b32_e32 v220, 16, v88
	v_and_b32_e32 v221, 0xffff0000, v88
	v_lshlrev_b32_e32 v222, 16, v89
	v_and_b32_e32 v223, 0xffff0000, v89
	v_lshlrev_b32_e32 v224, 16, v90
	v_and_b32_e32 v225, 0xffff0000, v90
	v_lshlrev_b32_e32 v226, 16, v91
	v_and_b32_e32 v227, 0xffff0000, v91
	v_mul_f32_e32 v220, v230, v220
	v_mul_f32_e32 v221, v230, v221
	v_mul_f32_e32 v222, v230, v222
	v_mul_f32_e32 v223, v230, v223
	v_mul_f32_e32 v224, v230, v224
	v_mul_f32_e32 v225, v230, v225
	v_mul_f32_e32 v226, v230, v226
	v_mul_f32_e32 v227, v230, v227
	v_fma_f32 v0, v229, v0, v220
	v_fma_f32 v1, v229, v1, v221
	v_fma_f32 v2, v229, v2, v222
	v_fma_f32 v3, v229, v3, v223
	v_fma_f32 v4, v229, v4, v224
	v_fma_f32 v5, v229, v5, v225
	v_fma_f32 v6, v229, v6, v226
	v_fma_f32 v7, v229, v7, v227
	s_add_i32 s13, s13, s10
	s_cmp_eq_u32 s13, s11
	s_cselect_b32 s13, s8, s13
	v_cvt_pk_bf16_f32 v216, v0, v1
	v_cvt_pk_bf16_f32 v217, v2, v3
	v_cvt_pk_bf16_f32 v218, v4, v5
	v_cvt_pk_bf16_f32 v219, v6, v7
	s_lshl_b32 s14, s13, 15
	s_add_u32 s16, s66, s14
	s_addc_u32 s17, s67, 0
	global_store_dwordx4 v236, v[216:219], s[16:17]
	v_readlane_b32 s18, v232, 21
	v_readlane_b32 s19, v233, 21
	s_nop 1
	v_add_f32_e32 v231, s18, v228
	v_max_f32_e32 v228, s19, v231
	v_sub_f32_e32 v231, v231, v228
	v_sub_f32_e32 v229, s19, v228
	v_mul_f32_e32 v231, 0x3fb8aa3b, v231
	v_mul_f32_e32 v229, 0x3fb8aa3b, v229
	v_exp_f32_e32 v230, v229
	v_exp_f32_e32 v229, v231
	s_nop 0
	v_lshlrev_b32_e32 v220, 16, v92
	v_and_b32_e32 v221, 0xffff0000, v92
	v_lshlrev_b32_e32 v222, 16, v93
	v_and_b32_e32 v223, 0xffff0000, v93
	v_lshlrev_b32_e32 v224, 16, v94
	v_and_b32_e32 v225, 0xffff0000, v94
	v_lshlrev_b32_e32 v226, 16, v95
	v_and_b32_e32 v227, 0xffff0000, v95
	v_mul_f32_e32 v220, v230, v220
	v_mul_f32_e32 v221, v230, v221
	v_mul_f32_e32 v222, v230, v222
	v_mul_f32_e32 v223, v230, v223
	v_mul_f32_e32 v224, v230, v224
	v_mul_f32_e32 v225, v230, v225
	v_mul_f32_e32 v226, v230, v226
	v_mul_f32_e32 v227, v230, v227
	v_fma_f32 v0, v229, v0, v220
	v_fma_f32 v1, v229, v1, v221
	v_fma_f32 v2, v229, v2, v222
	v_fma_f32 v3, v229, v3, v223
	v_fma_f32 v4, v229, v4, v224
	v_fma_f32 v5, v229, v5, v225
	v_fma_f32 v6, v229, v6, v226
	v_fma_f32 v7, v229, v7, v227
	s_add_i32 s13, s13, s10
	s_cmp_eq_u32 s13, s11
	s_cselect_b32 s13, s8, s13
	s_lshl_b32 s14, s12, 15
	s_add_u32 s16, s64, s14
	s_addc_u32 s17, s65, 0
	global_load_dwordx4 v[8:11], v236, s[16:17]
	s_add_i32 s12, s12, s10
	s_cmp_eq_u32 s12, s11
	s_cselect_b32 s12, s8, s12
	s_lshl_b32 s14, s12, 15
	s_add_u32 s16, s64, s14
	s_addc_u32 s17, s65, 0
	global_load_dwordx4 v[12:15], v236, s[16:17]
	s_add_i32 s12, s12, s10
	s_cmp_eq_u32 s12, s11
	s_cselect_b32 s12, s8, s12
	s_lshl_b32 s14, s12, 15
	s_add_u32 s16, s64, s14
	s_addc_u32 s17, s65, 0
	global_load_dwordx4 v[16:19], v236, s[16:17]
	s_add_i32 s12, s12, s10
	s_cmp_eq_u32 s12, s11
	s_cselect_b32 s12, s8, s12
	s_lshl_b32 s14, s12, 15
	s_add_u32 s16, s64, s14
	s_addc_u32 s17, s65, 0
	global_load_dwordx4 v[20:23], v236, s[16:17]
	s_add_i32 s12, s12, s10
	s_cmp_eq_u32 s12, s11
	s_cselect_b32 s12, s8, s12
	s_lshl_b32 s14, s12, 15
	s_add_u32 s16, s64, s14
	s_addc_u32 s17, s65, 0
	global_load_dwordx4 v[24:27], v236, s[16:17]
	s_add_i32 s12, s12, s10
	s_cmp_eq_u32 s12, s11
	s_cselect_b32 s12, s8, s12
	s_lshl_b32 s14, s12, 15
	s_add_u32 s16, s64, s14
	s_addc_u32 s17, s65, 0
	global_load_dwordx4 v[28:31], v236, s[16:17]
	s_add_i32 s12, s12, s10
	s_cmp_eq_u32 s12, s11
	s_cselect_b32 s12, s8, s12
	s_lshl_b32 s14, s12, 15
	s_add_u32 s16, s64, s14
	s_addc_u32 s17, s65, 0
	global_load_dwordx4 v[32:35], v236, s[16:17]
	s_add_i32 s12, s12, s10
	s_cmp_eq_u32 s12, s11
	s_cselect_b32 s12, s8, s12
	s_lshl_b32 s14, s12, 15
	s_add_u32 s16, s64, s14
	s_addc_u32 s17, s65, 0
	global_load_dwordx4 v[36:39], v236, s[16:17]
	s_add_i32 s12, s12, s10
	s_cmp_eq_u32 s12, s11
	s_cselect_b32 s12, s8, s12
	s_lshl_b32 s14, s12, 15
	s_add_u32 s16, s64, s14
	s_addc_u32 s17, s65, 0
	global_load_dwordx4 v[40:43], v236, s[16:17]
	s_add_i32 s12, s12, s10
	s_cmp_eq_u32 s12, s11
	s_cselect_b32 s12, s8, s12
	s_lshl_b32 s14, s12, 15
	s_add_u32 s16, s64, s14
	s_addc_u32 s17, s65, 0
	global_load_dwordx4 v[44:47], v236, s[16:17]
	s_add_i32 s12, s12, s10
	s_cmp_eq_u32 s12, s11
	s_cselect_b32 s12, s8, s12
	s_lshl_b32 s14, s12, 15
	s_add_u32 s16, s64, s14
	s_addc_u32 s17, s65, 0
	global_load_dwordx4 v[48:51], v236, s[16:17]
	s_add_i32 s12, s12, s10
	s_cmp_eq_u32 s12, s11
	s_cselect_b32 s12, s8, s12
	s_lshl_b32 s14, s12, 15
	s_add_u32 s16, s64, s14
	s_addc_u32 s17, s65, 0
	global_load_dwordx4 v[52:55], v236, s[16:17]
	s_add_i32 s12, s12, s10
	s_cmp_eq_u32 s12, s11
	s_cselect_b32 s12, s8, s12
	s_lshl_b32 s14, s12, 15
	s_add_u32 s16, s64, s14
	s_addc_u32 s17, s65, 0
	global_load_dwordx4 v[56:59], v236, s[16:17]
	s_add_i32 s12, s12, s10
	s_cmp_eq_u32 s12, s11
	s_cselect_b32 s12, s8, s12
	s_lshl_b32 s14, s12, 15
	s_add_u32 s16, s64, s14
	s_addc_u32 s17, s65, 0
	global_load_dwordx4 v[60:63], v236, s[16:17]
	s_add_i32 s12, s12, s10
	s_cmp_eq_u32 s12, s11
	s_cselect_b32 s12, s8, s12
	s_lshl_b32 s14, s12, 15
	s_add_u32 s16, s64, s14
	s_addc_u32 s17, s65, 0
	global_load_dwordx4 v[64:67], v236, s[16:17]
	s_add_i32 s12, s12, s10
	s_cmp_eq_u32 s12, s11
	s_cselect_b32 s12, s8, s12
	s_lshl_b32 s14, s12, 15
	s_add_u32 s16, s64, s14
	s_addc_u32 s17, s65, 0
	global_load_dwordx4 v[68:71], v236, s[16:17]
	s_add_i32 s12, s12, s10
	s_cmp_eq_u32 s12, s11
	s_cselect_b32 s12, s8, s12
	s_lshl_b32 s14, s12, 15
	s_add_u32 s16, s64, s14
	s_addc_u32 s17, s65, 0
	global_load_dwordx4 v[72:75], v236, s[16:17]
	s_add_i32 s12, s12, s10
	s_cmp_eq_u32 s12, s11
	s_cselect_b32 s12, s8, s12
	s_lshl_b32 s14, s12, 15
	s_add_u32 s16, s64, s14
	s_addc_u32 s17, s65, 0
	global_load_dwordx4 v[76:79], v236, s[16:17]
	s_add_i32 s12, s12, s10
	s_cmp_eq_u32 s12, s11
	s_cselect_b32 s12, s8, s12
	s_lshl_b32 s14, s12, 15
	s_add_u32 s16, s64, s14
	s_addc_u32 s17, s65, 0
	global_load_dwordx4 v[80:83], v236, s[16:17]
	s_add_i32 s12, s12, s10
	s_cmp_eq_u32 s12, s11
	s_cselect_b32 s12, s8, s12
	s_lshl_b32 s14, s12, 15
	s_add_u32 s16, s64, s14
	s_addc_u32 s17, s65, 0
	global_load_dwordx4 v[84:87], v236, s[16:17]
	s_add_i32 s12, s12, s10
	s_cmp_eq_u32 s12, s11
	s_cselect_b32 s12, s8, s12
	s_lshl_b32 s14, s12, 15
	s_add_u32 s16, s64, s14
	s_addc_u32 s17, s65, 0
	global_load_dwordx4 v[88:91], v236, s[16:17]
	s_add_i32 s12, s12, s10
	s_cmp_eq_u32 s12, s11
	s_cselect_b32 s12, s8, s12
	s_lshl_b32 s14, s12, 15
	s_add_u32 s16, s64, s14
	s_addc_u32 s17, s65, 0
	global_load_dwordx4 v[92:95], v236, s[16:17]
	s_add_i32 s12, s12, s10
	s_cmp_eq_u32 s12, s11
	s_cselect_b32 s12, s8, s12
	s_waitcnt vmcnt(22)
	v_cvt_pk_bf16_f32 v216, v0, v1
	v_cvt_pk_bf16_f32 v217, v2, v3
	v_cvt_pk_bf16_f32 v218, v4, v5
	v_cvt_pk_bf16_f32 v219, v6, v7
	s_lshl_b32 s14, s13, 15
	s_add_u32 s16, s66, s14
	s_addc_u32 s17, s67, 0
	global_store_dwordx4 v236, v[216:219], s[16:17]
	v_readlane_b32 s18, v232, 22
	v_readlane_b32 s19, v233, 22
	s_nop 1
	v_add_f32_e32 v231, s18, v228
	v_max_f32_e32 v228, s19, v231
	v_sub_f32_e32 v231, v231, v228
	v_sub_f32_e32 v229, s19, v228
	v_mul_f32_e32 v231, 0x3fb8aa3b, v231
	v_mul_f32_e32 v229, 0x3fb8aa3b, v229
	v_exp_f32_e32 v230, v229
	v_exp_f32_e32 v229, v231
	s_nop 0
	v_lshlrev_b32_e32 v220, 16, v96
	v_and_b32_e32 v221, 0xffff0000, v96
	v_lshlrev_b32_e32 v222, 16, v97
	v_and_b32_e32 v223, 0xffff0000, v97
	v_lshlrev_b32_e32 v224, 16, v98
	v_and_b32_e32 v225, 0xffff0000, v98
	v_lshlrev_b32_e32 v226, 16, v99
	v_and_b32_e32 v227, 0xffff0000, v99
	v_mul_f32_e32 v220, v230, v220
	v_mul_f32_e32 v221, v230, v221
	v_mul_f32_e32 v222, v230, v222
	v_mul_f32_e32 v223, v230, v223
	v_mul_f32_e32 v224, v230, v224
	v_mul_f32_e32 v225, v230, v225
	v_mul_f32_e32 v226, v230, v226
	v_mul_f32_e32 v227, v230, v227
	v_fma_f32 v0, v229, v0, v220
	v_fma_f32 v1, v229, v1, v221
	v_fma_f32 v2, v229, v2, v222
	v_fma_f32 v3, v229, v3, v223
	v_fma_f32 v4, v229, v4, v224
	v_fma_f32 v5, v229, v5, v225
	v_fma_f32 v6, v229, v6, v226
	v_fma_f32 v7, v229, v7, v227
	s_add_i32 s13, s13, s10
	s_cmp_eq_u32 s13, s11
	s_cselect_b32 s13, s8, s13
	v_cvt_pk_bf16_f32 v216, v0, v1
	v_cvt_pk_bf16_f32 v217, v2, v3
	v_cvt_pk_bf16_f32 v218, v4, v5
	v_cvt_pk_bf16_f32 v219, v6, v7
	s_lshl_b32 s14, s13, 15
	s_add_u32 s16, s66, s14
	s_addc_u32 s17, s67, 0
	global_store_dwordx4 v236, v[216:219], s[16:17]
	v_readlane_b32 s18, v232, 23
	v_readlane_b32 s19, v233, 23
	s_nop 1
	v_add_f32_e32 v231, s18, v228
	v_max_f32_e32 v228, s19, v231
	v_sub_f32_e32 v231, v231, v228
	v_sub_f32_e32 v229, s19, v228
	v_mul_f32_e32 v231, 0x3fb8aa3b, v231
	v_mul_f32_e32 v229, 0x3fb8aa3b, v229
	v_exp_f32_e32 v230, v229
	v_exp_f32_e32 v229, v231
	s_nop 0
	v_lshlrev_b32_e32 v220, 16, v100
	v_and_b32_e32 v221, 0xffff0000, v100
	v_lshlrev_b32_e32 v222, 16, v101
	v_and_b32_e32 v223, 0xffff0000, v101
	v_lshlrev_b32_e32 v224, 16, v102
	v_and_b32_e32 v225, 0xffff0000, v102
	v_lshlrev_b32_e32 v226, 16, v103
	v_and_b32_e32 v227, 0xffff0000, v103
	v_mul_f32_e32 v220, v230, v220
	v_mul_f32_e32 v221, v230, v221
	v_mul_f32_e32 v222, v230, v222
	v_mul_f32_e32 v223, v230, v223
	v_mul_f32_e32 v224, v230, v224
	v_mul_f32_e32 v225, v230, v225
	v_mul_f32_e32 v226, v230, v226
	v_mul_f32_e32 v227, v230, v227
	v_fma_f32 v0, v229, v0, v220
	v_fma_f32 v1, v229, v1, v221
	v_fma_f32 v2, v229, v2, v222
	v_fma_f32 v3, v229, v3, v223
	v_fma_f32 v4, v229, v4, v224
	v_fma_f32 v5, v229, v5, v225
	v_fma_f32 v6, v229, v6, v226
	v_fma_f32 v7, v229, v7, v227
	s_add_i32 s13, s13, s10
	s_cmp_eq_u32 s13, s11
	s_cselect_b32 s13, s8, s13
	v_cvt_pk_bf16_f32 v216, v0, v1
	v_cvt_pk_bf16_f32 v217, v2, v3
	v_cvt_pk_bf16_f32 v218, v4, v5
	v_cvt_pk_bf16_f32 v219, v6, v7
	s_lshl_b32 s14, s13, 15
	s_add_u32 s16, s66, s14
	s_addc_u32 s17, s67, 0
	global_store_dwordx4 v236, v[216:219], s[16:17]
	v_readlane_b32 s18, v232, 24
	v_readlane_b32 s19, v233, 24
	s_nop 1
	v_add_f32_e32 v231, s18, v228
	v_max_f32_e32 v228, s19, v231
	v_sub_f32_e32 v231, v231, v228
	v_sub_f32_e32 v229, s19, v228
	v_mul_f32_e32 v231, 0x3fb8aa3b, v231
	v_mul_f32_e32 v229, 0x3fb8aa3b, v229
	v_exp_f32_e32 v230, v229
	v_exp_f32_e32 v229, v231
	s_nop 0
	v_lshlrev_b32_e32 v220, 16, v104
	v_and_b32_e32 v221, 0xffff0000, v104
	v_lshlrev_b32_e32 v222, 16, v105
	v_and_b32_e32 v223, 0xffff0000, v105
	v_lshlrev_b32_e32 v224, 16, v106
	v_and_b32_e32 v225, 0xffff0000, v106
	v_lshlrev_b32_e32 v226, 16, v107
	v_and_b32_e32 v227, 0xffff0000, v107
	v_mul_f32_e32 v220, v230, v220
	v_mul_f32_e32 v221, v230, v221
	v_mul_f32_e32 v222, v230, v222
	v_mul_f32_e32 v223, v230, v223
	v_mul_f32_e32 v224, v230, v224
	v_mul_f32_e32 v225, v230, v225
	v_mul_f32_e32 v226, v230, v226
	v_mul_f32_e32 v227, v230, v227
	v_fma_f32 v0, v229, v0, v220
	v_fma_f32 v1, v229, v1, v221
	v_fma_f32 v2, v229, v2, v222
	v_fma_f32 v3, v229, v3, v223
	v_fma_f32 v4, v229, v4, v224
	v_fma_f32 v5, v229, v5, v225
	v_fma_f32 v6, v229, v6, v226
	v_fma_f32 v7, v229, v7, v227
	s_add_i32 s13, s13, s10
	s_cmp_eq_u32 s13, s11
	s_cselect_b32 s13, s8, s13
	v_cvt_pk_bf16_f32 v216, v0, v1
	v_cvt_pk_bf16_f32 v217, v2, v3
	v_cvt_pk_bf16_f32 v218, v4, v5
	v_cvt_pk_bf16_f32 v219, v6, v7
	s_lshl_b32 s14, s13, 15
	s_add_u32 s16, s66, s14
	s_addc_u32 s17, s67, 0
	global_store_dwordx4 v236, v[216:219], s[16:17]
	v_readlane_b32 s18, v232, 25
	v_readlane_b32 s19, v233, 25
	s_nop 1
	v_add_f32_e32 v231, s18, v228
	v_max_f32_e32 v228, s19, v231
	v_sub_f32_e32 v231, v231, v228
	v_sub_f32_e32 v229, s19, v228
	v_mul_f32_e32 v231, 0x3fb8aa3b, v231
	v_mul_f32_e32 v229, 0x3fb8aa3b, v229
	v_exp_f32_e32 v230, v229
	v_exp_f32_e32 v229, v231
	s_nop 0
	v_lshlrev_b32_e32 v220, 16, v108
	v_and_b32_e32 v221, 0xffff0000, v108
	v_lshlrev_b32_e32 v222, 16, v109
	v_and_b32_e32 v223, 0xffff0000, v109
	v_lshlrev_b32_e32 v224, 16, v110
	v_and_b32_e32 v225, 0xffff0000, v110
	v_lshlrev_b32_e32 v226, 16, v111
	v_and_b32_e32 v227, 0xffff0000, v111
	v_mul_f32_e32 v220, v230, v220
	v_mul_f32_e32 v221, v230, v221
	v_mul_f32_e32 v222, v230, v222
	v_mul_f32_e32 v223, v230, v223
	v_mul_f32_e32 v224, v230, v224
	v_mul_f32_e32 v225, v230, v225
	v_mul_f32_e32 v226, v230, v226
	v_mul_f32_e32 v227, v230, v227
	v_fma_f32 v0, v229, v0, v220
	v_fma_f32 v1, v229, v1, v221
	v_fma_f32 v2, v229, v2, v222
	v_fma_f32 v3, v229, v3, v223
	v_fma_f32 v4, v229, v4, v224
	v_fma_f32 v5, v229, v5, v225
	v_fma_f32 v6, v229, v6, v226
	v_fma_f32 v7, v229, v7, v227
	s_add_i32 s13, s13, s10
	s_cmp_eq_u32 s13, s11
	s_cselect_b32 s13, s8, s13
	v_cvt_pk_bf16_f32 v216, v0, v1
	v_cvt_pk_bf16_f32 v217, v2, v3
	v_cvt_pk_bf16_f32 v218, v4, v5
	v_cvt_pk_bf16_f32 v219, v6, v7
	s_lshl_b32 s14, s13, 15
	s_add_u32 s16, s66, s14
	s_addc_u32 s17, s67, 0
	global_store_dwordx4 v236, v[216:219], s[16:17]
	v_readlane_b32 s18, v232, 26
	v_readlane_b32 s19, v233, 26
	s_nop 1
	v_add_f32_e32 v231, s18, v228
	v_max_f32_e32 v228, s19, v231
	v_sub_f32_e32 v231, v231, v228
	v_sub_f32_e32 v229, s19, v228
	v_mul_f32_e32 v231, 0x3fb8aa3b, v231
	v_mul_f32_e32 v229, 0x3fb8aa3b, v229
	v_exp_f32_e32 v230, v229
	v_exp_f32_e32 v229, v231
	s_nop 0
	v_lshlrev_b32_e32 v220, 16, v112
	v_and_b32_e32 v221, 0xffff0000, v112
	v_lshlrev_b32_e32 v222, 16, v113
	v_and_b32_e32 v223, 0xffff0000, v113
	v_lshlrev_b32_e32 v224, 16, v114
	v_and_b32_e32 v225, 0xffff0000, v114
	v_lshlrev_b32_e32 v226, 16, v115
	v_and_b32_e32 v227, 0xffff0000, v115
	v_mul_f32_e32 v220, v230, v220
	v_mul_f32_e32 v221, v230, v221
	v_mul_f32_e32 v222, v230, v222
	v_mul_f32_e32 v223, v230, v223
	v_mul_f32_e32 v224, v230, v224
	v_mul_f32_e32 v225, v230, v225
	v_mul_f32_e32 v226, v230, v226
	v_mul_f32_e32 v227, v230, v227
	v_fma_f32 v0, v229, v0, v220
	v_fma_f32 v1, v229, v1, v221
	v_fma_f32 v2, v229, v2, v222
	v_fma_f32 v3, v229, v3, v223
	v_fma_f32 v4, v229, v4, v224
	v_fma_f32 v5, v229, v5, v225
	v_fma_f32 v6, v229, v6, v226
	v_fma_f32 v7, v229, v7, v227
	s_add_i32 s13, s13, s10
	s_cmp_eq_u32 s13, s11
	s_cselect_b32 s13, s8, s13
	v_cvt_pk_bf16_f32 v216, v0, v1
	v_cvt_pk_bf16_f32 v217, v2, v3
	v_cvt_pk_bf16_f32 v218, v4, v5
	v_cvt_pk_bf16_f32 v219, v6, v7
	s_lshl_b32 s14, s13, 15
	s_add_u32 s16, s66, s14
	s_addc_u32 s17, s67, 0
	global_store_dwordx4 v236, v[216:219], s[16:17]
	v_readlane_b32 s18, v232, 27
	v_readlane_b32 s19, v233, 27
	s_nop 1
	v_add_f32_e32 v231, s18, v228
	v_max_f32_e32 v228, s19, v231
	v_sub_f32_e32 v231, v231, v228
	v_sub_f32_e32 v229, s19, v228
	v_mul_f32_e32 v231, 0x3fb8aa3b, v231
	v_mul_f32_e32 v229, 0x3fb8aa3b, v229
	v_exp_f32_e32 v230, v229
	v_exp_f32_e32 v229, v231
	s_nop 0
	v_lshlrev_b32_e32 v220, 16, v116
	v_and_b32_e32 v221, 0xffff0000, v116
	v_lshlrev_b32_e32 v222, 16, v117
	v_and_b32_e32 v223, 0xffff0000, v117
	v_lshlrev_b32_e32 v224, 16, v118
	v_and_b32_e32 v225, 0xffff0000, v118
	v_lshlrev_b32_e32 v226, 16, v119
	v_and_b32_e32 v227, 0xffff0000, v119
	v_mul_f32_e32 v220, v230, v220
	v_mul_f32_e32 v221, v230, v221
	v_mul_f32_e32 v222, v230, v222
	v_mul_f32_e32 v223, v230, v223
	v_mul_f32_e32 v224, v230, v224
	v_mul_f32_e32 v225, v230, v225
	v_mul_f32_e32 v226, v230, v226
	v_mul_f32_e32 v227, v230, v227
	v_fma_f32 v0, v229, v0, v220
	v_fma_f32 v1, v229, v1, v221
	v_fma_f32 v2, v229, v2, v222
	v_fma_f32 v3, v229, v3, v223
	v_fma_f32 v4, v229, v4, v224
	v_fma_f32 v5, v229, v5, v225
	v_fma_f32 v6, v229, v6, v226
	v_fma_f32 v7, v229, v7, v227
	s_add_i32 s13, s13, s10
	s_cmp_eq_u32 s13, s11
	s_cselect_b32 s13, s8, s13
	v_cvt_pk_bf16_f32 v216, v0, v1
	v_cvt_pk_bf16_f32 v217, v2, v3
	v_cvt_pk_bf16_f32 v218, v4, v5
	v_cvt_pk_bf16_f32 v219, v6, v7
	s_lshl_b32 s14, s13, 15
	s_add_u32 s16, s66, s14
	s_addc_u32 s17, s67, 0
	global_store_dwordx4 v236, v[216:219], s[16:17]
	v_readlane_b32 s18, v232, 28
	v_readlane_b32 s19, v233, 28
	s_nop 1
	v_add_f32_e32 v231, s18, v228
	v_max_f32_e32 v228, s19, v231
	v_sub_f32_e32 v231, v231, v228
	v_sub_f32_e32 v229, s19, v228
	v_mul_f32_e32 v231, 0x3fb8aa3b, v231
	v_mul_f32_e32 v229, 0x3fb8aa3b, v229
	v_exp_f32_e32 v230, v229
	v_exp_f32_e32 v229, v231
	s_nop 0
	v_lshlrev_b32_e32 v220, 16, v120
	v_and_b32_e32 v221, 0xffff0000, v120
	v_lshlrev_b32_e32 v222, 16, v121
	v_and_b32_e32 v223, 0xffff0000, v121
	v_lshlrev_b32_e32 v224, 16, v122
	v_and_b32_e32 v225, 0xffff0000, v122
	v_lshlrev_b32_e32 v226, 16, v123
	v_and_b32_e32 v227, 0xffff0000, v123
	v_mul_f32_e32 v220, v230, v220
	v_mul_f32_e32 v221, v230, v221
	v_mul_f32_e32 v222, v230, v222
	v_mul_f32_e32 v223, v230, v223
	v_mul_f32_e32 v224, v230, v224
	v_mul_f32_e32 v225, v230, v225
	v_mul_f32_e32 v226, v230, v226
	v_mul_f32_e32 v227, v230, v227
	v_fma_f32 v0, v229, v0, v220
	v_fma_f32 v1, v229, v1, v221
	v_fma_f32 v2, v229, v2, v222
	v_fma_f32 v3, v229, v3, v223
	v_fma_f32 v4, v229, v4, v224
	v_fma_f32 v5, v229, v5, v225
	v_fma_f32 v6, v229, v6, v226
	v_fma_f32 v7, v229, v7, v227
	s_add_i32 s13, s13, s10
	s_cmp_eq_u32 s13, s11
	s_cselect_b32 s13, s8, s13
	v_cvt_pk_bf16_f32 v216, v0, v1
	v_cvt_pk_bf16_f32 v217, v2, v3
	v_cvt_pk_bf16_f32 v218, v4, v5
	v_cvt_pk_bf16_f32 v219, v6, v7
	s_lshl_b32 s14, s13, 15
	s_add_u32 s16, s66, s14
	s_addc_u32 s17, s67, 0
	global_store_dwordx4 v236, v[216:219], s[16:17]
	v_readlane_b32 s18, v232, 29
	v_readlane_b32 s19, v233, 29
	s_nop 1
	v_add_f32_e32 v231, s18, v228
	v_max_f32_e32 v228, s19, v231
	v_sub_f32_e32 v231, v231, v228
	v_sub_f32_e32 v229, s19, v228
	v_mul_f32_e32 v231, 0x3fb8aa3b, v231
	v_mul_f32_e32 v229, 0x3fb8aa3b, v229
	v_exp_f32_e32 v230, v229
	v_exp_f32_e32 v229, v231
	s_nop 0
	v_lshlrev_b32_e32 v220, 16, v124
	v_and_b32_e32 v221, 0xffff0000, v124
	v_lshlrev_b32_e32 v222, 16, v125
	v_and_b32_e32 v223, 0xffff0000, v125
	v_lshlrev_b32_e32 v224, 16, v126
	v_and_b32_e32 v225, 0xffff0000, v126
	v_lshlrev_b32_e32 v226, 16, v127
	v_and_b32_e32 v227, 0xffff0000, v127
	v_mul_f32_e32 v220, v230, v220
	v_mul_f32_e32 v221, v230, v221
	v_mul_f32_e32 v222, v230, v222
	v_mul_f32_e32 v223, v230, v223
	v_mul_f32_e32 v224, v230, v224
	v_mul_f32_e32 v225, v230, v225
	v_mul_f32_e32 v226, v230, v226
	v_mul_f32_e32 v227, v230, v227
	v_fma_f32 v0, v229, v0, v220
	v_fma_f32 v1, v229, v1, v221
	v_fma_f32 v2, v229, v2, v222
	v_fma_f32 v3, v229, v3, v223
	v_fma_f32 v4, v229, v4, v224
	v_fma_f32 v5, v229, v5, v225
	v_fma_f32 v6, v229, v6, v226
	v_fma_f32 v7, v229, v7, v227
	s_add_i32 s13, s13, s10
	s_cmp_eq_u32 s13, s11
	s_cselect_b32 s13, s8, s13
	v_cvt_pk_bf16_f32 v216, v0, v1
	v_cvt_pk_bf16_f32 v217, v2, v3
	v_cvt_pk_bf16_f32 v218, v4, v5
	v_cvt_pk_bf16_f32 v219, v6, v7
	s_lshl_b32 s14, s13, 15
	s_add_u32 s16, s66, s14
	s_addc_u32 s17, s67, 0
	global_store_dwordx4 v236, v[216:219], s[16:17]
	v_readlane_b32 s18, v232, 30
	v_readlane_b32 s19, v233, 30
	s_nop 1
	v_add_f32_e32 v231, s18, v228
	v_max_f32_e32 v228, s19, v231
	v_sub_f32_e32 v231, v231, v228
	v_sub_f32_e32 v229, s19, v228
	v_mul_f32_e32 v231, 0x3fb8aa3b, v231
	v_mul_f32_e32 v229, 0x3fb8aa3b, v229
	v_exp_f32_e32 v230, v229
	v_exp_f32_e32 v229, v231
	s_nop 0
	v_lshlrev_b32_e32 v220, 16, v130
	v_and_b32_e32 v221, 0xffff0000, v130
	v_lshlrev_b32_e32 v222, 16, v131
	v_and_b32_e32 v223, 0xffff0000, v131
	v_lshlrev_b32_e32 v224, 16, v132
	v_and_b32_e32 v225, 0xffff0000, v132
	v_lshlrev_b32_e32 v226, 16, v133
	v_and_b32_e32 v227, 0xffff0000, v133
	v_mul_f32_e32 v220, v230, v220
	v_mul_f32_e32 v221, v230, v221
	v_mul_f32_e32 v222, v230, v222
	v_mul_f32_e32 v223, v230, v223
	v_mul_f32_e32 v224, v230, v224
	v_mul_f32_e32 v225, v230, v225
	v_mul_f32_e32 v226, v230, v226
	v_mul_f32_e32 v227, v230, v227
	v_fma_f32 v0, v229, v0, v220
	v_fma_f32 v1, v229, v1, v221
	v_fma_f32 v2, v229, v2, v222
	v_fma_f32 v3, v229, v3, v223
	v_fma_f32 v4, v229, v4, v224
	v_fma_f32 v5, v229, v5, v225
	v_fma_f32 v6, v229, v6, v226
	v_fma_f32 v7, v229, v7, v227
	s_add_i32 s13, s13, s10
	s_cmp_eq_u32 s13, s11
	s_cselect_b32 s13, s8, s13
	v_cvt_pk_bf16_f32 v216, v0, v1
	v_cvt_pk_bf16_f32 v217, v2, v3
	v_cvt_pk_bf16_f32 v218, v4, v5
	v_cvt_pk_bf16_f32 v219, v6, v7
	s_lshl_b32 s14, s13, 15
	s_add_u32 s16, s66, s14
	s_addc_u32 s17, s67, 0
	global_store_dwordx4 v236, v[216:219], s[16:17]
	v_readlane_b32 s18, v232, 31
	v_readlane_b32 s19, v233, 31
	s_nop 1
	v_add_f32_e32 v231, s18, v228
	v_max_f32_e32 v228, s19, v231
	v_sub_f32_e32 v231, v231, v228
	v_sub_f32_e32 v229, s19, v228
	v_mul_f32_e32 v231, 0x3fb8aa3b, v231
	v_mul_f32_e32 v229, 0x3fb8aa3b, v229
	v_exp_f32_e32 v230, v229
	v_exp_f32_e32 v229, v231
	s_nop 0
	v_lshlrev_b32_e32 v220, 16, v134
	v_and_b32_e32 v221, 0xffff0000, v134
	v_lshlrev_b32_e32 v222, 16, v135
	v_and_b32_e32 v223, 0xffff0000, v135
	v_lshlrev_b32_e32 v224, 16, v136
	v_and_b32_e32 v225, 0xffff0000, v136
	v_lshlrev_b32_e32 v226, 16, v137
	v_and_b32_e32 v227, 0xffff0000, v137
	v_mul_f32_e32 v220, v230, v220
	v_mul_f32_e32 v221, v230, v221
	v_mul_f32_e32 v222, v230, v222
	v_mul_f32_e32 v223, v230, v223
	v_mul_f32_e32 v224, v230, v224
	v_mul_f32_e32 v225, v230, v225
	v_mul_f32_e32 v226, v230, v226
	v_mul_f32_e32 v227, v230, v227
	v_fma_f32 v0, v229, v0, v220
	v_fma_f32 v1, v229, v1, v221
	v_fma_f32 v2, v229, v2, v222
	v_fma_f32 v3, v229, v3, v223
	v_fma_f32 v4, v229, v4, v224
	v_fma_f32 v5, v229, v5, v225
	v_fma_f32 v6, v229, v6, v226
	v_fma_f32 v7, v229, v7, v227
	s_add_i32 s13, s13, s10
	s_cmp_eq_u32 s13, s11
	s_cselect_b32 s13, s8, s13
	v_cvt_pk_bf16_f32 v216, v0, v1
	v_cvt_pk_bf16_f32 v217, v2, v3
	v_cvt_pk_bf16_f32 v218, v4, v5
	v_cvt_pk_bf16_f32 v219, v6, v7
	s_lshl_b32 s14, s13, 15
	s_add_u32 s16, s66, s14
	s_addc_u32 s17, s67, 0
	global_store_dwordx4 v236, v[216:219], s[16:17]
	v_readlane_b32 s18, v232, 32
	v_readlane_b32 s19, v233, 32
	s_nop 1
	v_add_f32_e32 v231, s18, v228
	v_max_f32_e32 v228, s19, v231
	v_sub_f32_e32 v231, v231, v228
	v_sub_f32_e32 v229, s19, v228
	v_mul_f32_e32 v231, 0x3fb8aa3b, v231
	v_mul_f32_e32 v229, 0x3fb8aa3b, v229
	v_exp_f32_e32 v230, v229
	v_exp_f32_e32 v229, v231
	s_nop 0
	v_lshlrev_b32_e32 v220, 16, v138
	v_and_b32_e32 v221, 0xffff0000, v138
	v_lshlrev_b32_e32 v222, 16, v139
	v_and_b32_e32 v223, 0xffff0000, v139
	v_lshlrev_b32_e32 v224, 16, v140
	v_and_b32_e32 v225, 0xffff0000, v140
	v_lshlrev_b32_e32 v226, 16, v141
	v_and_b32_e32 v227, 0xffff0000, v141
	v_mul_f32_e32 v220, v230, v220
	v_mul_f32_e32 v221, v230, v221
	v_mul_f32_e32 v222, v230, v222
	v_mul_f32_e32 v223, v230, v223
	v_mul_f32_e32 v224, v230, v224
	v_mul_f32_e32 v225, v230, v225
	v_mul_f32_e32 v226, v230, v226
	v_mul_f32_e32 v227, v230, v227
	v_fma_f32 v0, v229, v0, v220
	v_fma_f32 v1, v229, v1, v221
	v_fma_f32 v2, v229, v2, v222
	v_fma_f32 v3, v229, v3, v223
	v_fma_f32 v4, v229, v4, v224
	v_fma_f32 v5, v229, v5, v225
	v_fma_f32 v6, v229, v6, v226
	v_fma_f32 v7, v229, v7, v227
	s_add_i32 s13, s13, s10
	s_cmp_eq_u32 s13, s11
	s_cselect_b32 s13, s8, s13
	v_cvt_pk_bf16_f32 v216, v0, v1
	v_cvt_pk_bf16_f32 v217, v2, v3
	v_cvt_pk_bf16_f32 v218, v4, v5
	v_cvt_pk_bf16_f32 v219, v6, v7
	s_lshl_b32 s14, s13, 15
	s_add_u32 s16, s66, s14
	s_addc_u32 s17, s67, 0
	global_store_dwordx4 v236, v[216:219], s[16:17]
	v_readlane_b32 s18, v232, 33
	v_readlane_b32 s19, v233, 33
	s_nop 1
	v_add_f32_e32 v231, s18, v228
	v_max_f32_e32 v228, s19, v231
	v_sub_f32_e32 v231, v231, v228
	v_sub_f32_e32 v229, s19, v228
	v_mul_f32_e32 v231, 0x3fb8aa3b, v231
	v_mul_f32_e32 v229, 0x3fb8aa3b, v229
	v_exp_f32_e32 v230, v229
	v_exp_f32_e32 v229, v231
	s_nop 0
	v_lshlrev_b32_e32 v220, 16, v142
	v_and_b32_e32 v221, 0xffff0000, v142
	v_lshlrev_b32_e32 v222, 16, v143
	v_and_b32_e32 v223, 0xffff0000, v143
	v_lshlrev_b32_e32 v224, 16, v144
	v_and_b32_e32 v225, 0xffff0000, v144
	v_lshlrev_b32_e32 v226, 16, v145
	v_and_b32_e32 v227, 0xffff0000, v145
	v_mul_f32_e32 v220, v230, v220
	v_mul_f32_e32 v221, v230, v221
	v_mul_f32_e32 v222, v230, v222
	v_mul_f32_e32 v223, v230, v223
	v_mul_f32_e32 v224, v230, v224
	v_mul_f32_e32 v225, v230, v225
	v_mul_f32_e32 v226, v230, v226
	v_mul_f32_e32 v227, v230, v227
	v_fma_f32 v0, v229, v0, v220
	v_fma_f32 v1, v229, v1, v221
	v_fma_f32 v2, v229, v2, v222
	v_fma_f32 v3, v229, v3, v223
	v_fma_f32 v4, v229, v4, v224
	v_fma_f32 v5, v229, v5, v225
	v_fma_f32 v6, v229, v6, v226
	v_fma_f32 v7, v229, v7, v227
	s_add_i32 s13, s13, s10
	s_cmp_eq_u32 s13, s11
	s_cselect_b32 s13, s8, s13
	v_cvt_pk_bf16_f32 v216, v0, v1
	v_cvt_pk_bf16_f32 v217, v2, v3
	v_cvt_pk_bf16_f32 v218, v4, v5
	v_cvt_pk_bf16_f32 v219, v6, v7
	s_lshl_b32 s14, s13, 15
	s_add_u32 s16, s66, s14
	s_addc_u32 s17, s67, 0
	global_store_dwordx4 v236, v[216:219], s[16:17]
	v_readlane_b32 s18, v232, 34
	v_readlane_b32 s19, v233, 34
	s_nop 1
	v_add_f32_e32 v231, s18, v228
	v_max_f32_e32 v228, s19, v231
	v_sub_f32_e32 v231, v231, v228
	v_sub_f32_e32 v229, s19, v228
	v_mul_f32_e32 v231, 0x3fb8aa3b, v231
	v_mul_f32_e32 v229, 0x3fb8aa3b, v229
	v_exp_f32_e32 v230, v229
	v_exp_f32_e32 v229, v231
	s_nop 0
	v_lshlrev_b32_e32 v220, 16, v146
	v_and_b32_e32 v221, 0xffff0000, v146
	v_lshlrev_b32_e32 v222, 16, v147
	v_and_b32_e32 v223, 0xffff0000, v147
	v_lshlrev_b32_e32 v224, 16, v148
	v_and_b32_e32 v225, 0xffff0000, v148
	v_lshlrev_b32_e32 v226, 16, v149
	v_and_b32_e32 v227, 0xffff0000, v149
	v_mul_f32_e32 v220, v230, v220
	v_mul_f32_e32 v221, v230, v221
	v_mul_f32_e32 v222, v230, v222
	v_mul_f32_e32 v223, v230, v223
	v_mul_f32_e32 v224, v230, v224
	v_mul_f32_e32 v225, v230, v225
	v_mul_f32_e32 v226, v230, v226
	v_mul_f32_e32 v227, v230, v227
	v_fma_f32 v0, v229, v0, v220
	v_fma_f32 v1, v229, v1, v221
	v_fma_f32 v2, v229, v2, v222
	v_fma_f32 v3, v229, v3, v223
	v_fma_f32 v4, v229, v4, v224
	v_fma_f32 v5, v229, v5, v225
	v_fma_f32 v6, v229, v6, v226
	v_fma_f32 v7, v229, v7, v227
	s_add_i32 s13, s13, s10
	s_cmp_eq_u32 s13, s11
	s_cselect_b32 s13, s8, s13
	v_cvt_pk_bf16_f32 v216, v0, v1
	v_cvt_pk_bf16_f32 v217, v2, v3
	v_cvt_pk_bf16_f32 v218, v4, v5
	v_cvt_pk_bf16_f32 v219, v6, v7
	s_lshl_b32 s14, s13, 15
	s_add_u32 s16, s66, s14
	s_addc_u32 s17, s67, 0
	global_store_dwordx4 v236, v[216:219], s[16:17]
	v_readlane_b32 s18, v232, 35
	v_readlane_b32 s19, v233, 35
	s_nop 1
	v_add_f32_e32 v231, s18, v228
	v_max_f32_e32 v228, s19, v231
	v_sub_f32_e32 v231, v231, v228
	v_sub_f32_e32 v229, s19, v228
	v_mul_f32_e32 v231, 0x3fb8aa3b, v231
	v_mul_f32_e32 v229, 0x3fb8aa3b, v229
	v_exp_f32_e32 v230, v229
	v_exp_f32_e32 v229, v231
	s_nop 0
	v_lshlrev_b32_e32 v220, 16, v150
	v_and_b32_e32 v221, 0xffff0000, v150
	v_lshlrev_b32_e32 v222, 16, v151
	v_and_b32_e32 v223, 0xffff0000, v151
	v_lshlrev_b32_e32 v224, 16, v152
	v_and_b32_e32 v225, 0xffff0000, v152
	v_lshlrev_b32_e32 v226, 16, v153
	v_and_b32_e32 v227, 0xffff0000, v153
	v_mul_f32_e32 v220, v230, v220
	v_mul_f32_e32 v221, v230, v221
	v_mul_f32_e32 v222, v230, v222
	v_mul_f32_e32 v223, v230, v223
	v_mul_f32_e32 v224, v230, v224
	v_mul_f32_e32 v225, v230, v225
	v_mul_f32_e32 v226, v230, v226
	v_mul_f32_e32 v227, v230, v227
	v_fma_f32 v0, v229, v0, v220
	v_fma_f32 v1, v229, v1, v221
	v_fma_f32 v2, v229, v2, v222
	v_fma_f32 v3, v229, v3, v223
	v_fma_f32 v4, v229, v4, v224
	v_fma_f32 v5, v229, v5, v225
	v_fma_f32 v6, v229, v6, v226
	v_fma_f32 v7, v229, v7, v227
	s_add_i32 s13, s13, s10
	s_cmp_eq_u32 s13, s11
	s_cselect_b32 s13, s8, s13
	v_cvt_pk_bf16_f32 v216, v0, v1
	v_cvt_pk_bf16_f32 v217, v2, v3
	v_cvt_pk_bf16_f32 v218, v4, v5
	v_cvt_pk_bf16_f32 v219, v6, v7
	s_lshl_b32 s14, s13, 15
	s_add_u32 s16, s66, s14
	s_addc_u32 s17, s67, 0
	global_store_dwordx4 v236, v[216:219], s[16:17]
	v_readlane_b32 s18, v232, 36
	v_readlane_b32 s19, v233, 36
	s_nop 1
	v_add_f32_e32 v231, s18, v228
	v_max_f32_e32 v228, s19, v231
	v_sub_f32_e32 v231, v231, v228
	v_sub_f32_e32 v229, s19, v228
	v_mul_f32_e32 v231, 0x3fb8aa3b, v231
	v_mul_f32_e32 v229, 0x3fb8aa3b, v229
	v_exp_f32_e32 v230, v229
	v_exp_f32_e32 v229, v231
	s_nop 0
	v_lshlrev_b32_e32 v220, 16, v154
	v_and_b32_e32 v221, 0xffff0000, v154
	v_lshlrev_b32_e32 v222, 16, v155
	v_and_b32_e32 v223, 0xffff0000, v155
	v_lshlrev_b32_e32 v224, 16, v156
	v_and_b32_e32 v225, 0xffff0000, v156
	v_lshlrev_b32_e32 v226, 16, v157
	v_and_b32_e32 v227, 0xffff0000, v157
	v_mul_f32_e32 v220, v230, v220
	v_mul_f32_e32 v221, v230, v221
	v_mul_f32_e32 v222, v230, v222
	v_mul_f32_e32 v223, v230, v223
	v_mul_f32_e32 v224, v230, v224
	v_mul_f32_e32 v225, v230, v225
	v_mul_f32_e32 v226, v230, v226
	v_mul_f32_e32 v227, v230, v227
	v_fma_f32 v0, v229, v0, v220
	v_fma_f32 v1, v229, v1, v221
	v_fma_f32 v2, v229, v2, v222
	v_fma_f32 v3, v229, v3, v223
	v_fma_f32 v4, v229, v4, v224
	v_fma_f32 v5, v229, v5, v225
	v_fma_f32 v6, v229, v6, v226
	v_fma_f32 v7, v229, v7, v227
	s_add_i32 s13, s13, s10
	s_cmp_eq_u32 s13, s11
	s_cselect_b32 s13, s8, s13
	v_cvt_pk_bf16_f32 v216, v0, v1
	v_cvt_pk_bf16_f32 v217, v2, v3
	v_cvt_pk_bf16_f32 v218, v4, v5
	v_cvt_pk_bf16_f32 v219, v6, v7
	s_lshl_b32 s14, s13, 15
	s_add_u32 s16, s66, s14
	s_addc_u32 s17, s67, 0
	global_store_dwordx4 v236, v[216:219], s[16:17]
	v_readlane_b32 s18, v232, 37
	v_readlane_b32 s19, v233, 37
	s_nop 1
	v_add_f32_e32 v231, s18, v228
	v_max_f32_e32 v228, s19, v231
	v_sub_f32_e32 v231, v231, v228
	v_sub_f32_e32 v229, s19, v228
	v_mul_f32_e32 v231, 0x3fb8aa3b, v231
	v_mul_f32_e32 v229, 0x3fb8aa3b, v229
	v_exp_f32_e32 v230, v229
	v_exp_f32_e32 v229, v231
	s_nop 0
	v_lshlrev_b32_e32 v220, 16, v158
	v_and_b32_e32 v221, 0xffff0000, v158
	v_lshlrev_b32_e32 v222, 16, v159
	v_and_b32_e32 v223, 0xffff0000, v159
	v_lshlrev_b32_e32 v224, 16, v160
	v_and_b32_e32 v225, 0xffff0000, v160
	v_lshlrev_b32_e32 v226, 16, v161
	v_and_b32_e32 v227, 0xffff0000, v161
	v_mul_f32_e32 v220, v230, v220
	v_mul_f32_e32 v221, v230, v221
	v_mul_f32_e32 v222, v230, v222
	v_mul_f32_e32 v223, v230, v223
	v_mul_f32_e32 v224, v230, v224
	v_mul_f32_e32 v225, v230, v225
	v_mul_f32_e32 v226, v230, v226
	v_mul_f32_e32 v227, v230, v227
	v_fma_f32 v0, v229, v0, v220
	v_fma_f32 v1, v229, v1, v221
	v_fma_f32 v2, v229, v2, v222
	v_fma_f32 v3, v229, v3, v223
	v_fma_f32 v4, v229, v4, v224
	v_fma_f32 v5, v229, v5, v225
	v_fma_f32 v6, v229, v6, v226
	v_fma_f32 v7, v229, v7, v227
	s_add_i32 s13, s13, s10
	s_cmp_eq_u32 s13, s11
	s_cselect_b32 s13, s8, s13
	v_cvt_pk_bf16_f32 v216, v0, v1
	v_cvt_pk_bf16_f32 v217, v2, v3
	v_cvt_pk_bf16_f32 v218, v4, v5
	v_cvt_pk_bf16_f32 v219, v6, v7
	s_lshl_b32 s14, s13, 15
	s_add_u32 s16, s66, s14
	s_addc_u32 s17, s67, 0
	global_store_dwordx4 v236, v[216:219], s[16:17]
	v_readlane_b32 s18, v232, 38
	v_readlane_b32 s19, v233, 38
	s_nop 1
	v_add_f32_e32 v231, s18, v228
	v_max_f32_e32 v228, s19, v231
	v_sub_f32_e32 v231, v231, v228
	v_sub_f32_e32 v229, s19, v228
	v_mul_f32_e32 v231, 0x3fb8aa3b, v231
	v_mul_f32_e32 v229, 0x3fb8aa3b, v229
	v_exp_f32_e32 v230, v229
	v_exp_f32_e32 v229, v231
	s_nop 0
	v_lshlrev_b32_e32 v220, 16, v188
	v_and_b32_e32 v221, 0xffff0000, v188
	v_lshlrev_b32_e32 v222, 16, v189
	v_and_b32_e32 v223, 0xffff0000, v189
	v_lshlrev_b32_e32 v224, 16, v190
	v_and_b32_e32 v225, 0xffff0000, v190
	v_lshlrev_b32_e32 v226, 16, v191
	v_and_b32_e32 v227, 0xffff0000, v191
	v_mul_f32_e32 v220, v230, v220
	v_mul_f32_e32 v221, v230, v221
	v_mul_f32_e32 v222, v230, v222
	v_mul_f32_e32 v223, v230, v223
	v_mul_f32_e32 v224, v230, v224
	v_mul_f32_e32 v225, v230, v225
	v_mul_f32_e32 v226, v230, v226
	v_mul_f32_e32 v227, v230, v227
	v_fma_f32 v0, v229, v0, v220
	v_fma_f32 v1, v229, v1, v221
	v_fma_f32 v2, v229, v2, v222
	v_fma_f32 v3, v229, v3, v223
	v_fma_f32 v4, v229, v4, v224
	v_fma_f32 v5, v229, v5, v225
	v_fma_f32 v6, v229, v6, v226
	v_fma_f32 v7, v229, v7, v227
	s_add_i32 s13, s13, s10
	s_cmp_eq_u32 s13, s11
	s_cselect_b32 s13, s8, s13
	v_cvt_pk_bf16_f32 v216, v0, v1
	v_cvt_pk_bf16_f32 v217, v2, v3
	v_cvt_pk_bf16_f32 v218, v4, v5
	v_cvt_pk_bf16_f32 v219, v6, v7
	s_lshl_b32 s14, s13, 15
	s_add_u32 s16, s66, s14
	s_addc_u32 s17, s67, 0
	global_store_dwordx4 v236, v[216:219], s[16:17]
	v_readlane_b32 s18, v232, 39
	v_readlane_b32 s19, v233, 39
	s_nop 1
	v_add_f32_e32 v231, s18, v228
	v_max_f32_e32 v228, s19, v231
	v_sub_f32_e32 v231, v231, v228
	v_sub_f32_e32 v229, s19, v228
	v_mul_f32_e32 v231, 0x3fb8aa3b, v231
	v_mul_f32_e32 v229, 0x3fb8aa3b, v229
	v_exp_f32_e32 v230, v229
	v_exp_f32_e32 v229, v231
	s_nop 0
	v_lshlrev_b32_e32 v220, 16, v192
	v_and_b32_e32 v221, 0xffff0000, v192
	v_lshlrev_b32_e32 v222, 16, v193
	v_and_b32_e32 v223, 0xffff0000, v193
	v_lshlrev_b32_e32 v224, 16, v194
	v_and_b32_e32 v225, 0xffff0000, v194
	v_lshlrev_b32_e32 v226, 16, v195
	v_and_b32_e32 v227, 0xffff0000, v195
	v_mul_f32_e32 v220, v230, v220
	v_mul_f32_e32 v221, v230, v221
	v_mul_f32_e32 v222, v230, v222
	v_mul_f32_e32 v223, v230, v223
	v_mul_f32_e32 v224, v230, v224
	v_mul_f32_e32 v225, v230, v225
	v_mul_f32_e32 v226, v230, v226
	v_mul_f32_e32 v227, v230, v227
	v_fma_f32 v0, v229, v0, v220
	v_fma_f32 v1, v229, v1, v221
	v_fma_f32 v2, v229, v2, v222
	v_fma_f32 v3, v229, v3, v223
	v_fma_f32 v4, v229, v4, v224
	v_fma_f32 v5, v229, v5, v225
	v_fma_f32 v6, v229, v6, v226
	v_fma_f32 v7, v229, v7, v227
	s_add_i32 s13, s13, s10
	s_cmp_eq_u32 s13, s11
	s_cselect_b32 s13, s8, s13
	v_cvt_pk_bf16_f32 v216, v0, v1
	v_cvt_pk_bf16_f32 v217, v2, v3
	v_cvt_pk_bf16_f32 v218, v4, v5
	v_cvt_pk_bf16_f32 v219, v6, v7
	s_lshl_b32 s14, s13, 15
	s_add_u32 s16, s66, s14
	s_addc_u32 s17, s67, 0
	global_store_dwordx4 v236, v[216:219], s[16:17]
	v_readlane_b32 s18, v232, 40
	v_readlane_b32 s19, v233, 40
	s_nop 1
	v_add_f32_e32 v231, s18, v228
	v_max_f32_e32 v228, s19, v231
	v_sub_f32_e32 v231, v231, v228
	v_sub_f32_e32 v229, s19, v228
	v_mul_f32_e32 v231, 0x3fb8aa3b, v231
	v_mul_f32_e32 v229, 0x3fb8aa3b, v229
	v_exp_f32_e32 v230, v229
	v_exp_f32_e32 v229, v231
	s_nop 0
	v_lshlrev_b32_e32 v220, 16, v196
	v_and_b32_e32 v221, 0xffff0000, v196
	v_lshlrev_b32_e32 v222, 16, v197
	v_and_b32_e32 v223, 0xffff0000, v197
	v_lshlrev_b32_e32 v224, 16, v198
	v_and_b32_e32 v225, 0xffff0000, v198
	v_lshlrev_b32_e32 v226, 16, v199
	v_and_b32_e32 v227, 0xffff0000, v199
	v_mul_f32_e32 v220, v230, v220
	v_mul_f32_e32 v221, v230, v221
	v_mul_f32_e32 v222, v230, v222
	v_mul_f32_e32 v223, v230, v223
	v_mul_f32_e32 v224, v230, v224
	v_mul_f32_e32 v225, v230, v225
	v_mul_f32_e32 v226, v230, v226
	v_mul_f32_e32 v227, v230, v227
	v_fma_f32 v0, v229, v0, v220
	v_fma_f32 v1, v229, v1, v221
	v_fma_f32 v2, v229, v2, v222
	v_fma_f32 v3, v229, v3, v223
	v_fma_f32 v4, v229, v4, v224
	v_fma_f32 v5, v229, v5, v225
	v_fma_f32 v6, v229, v6, v226
	v_fma_f32 v7, v229, v7, v227
	s_add_i32 s13, s13, s10
	s_cmp_eq_u32 s13, s11
	s_cselect_b32 s13, s8, s13
	v_cvt_pk_bf16_f32 v216, v0, v1
	v_cvt_pk_bf16_f32 v217, v2, v3
	v_cvt_pk_bf16_f32 v218, v4, v5
	v_cvt_pk_bf16_f32 v219, v6, v7
	s_lshl_b32 s14, s13, 15
	s_add_u32 s16, s66, s14
	s_addc_u32 s17, s67, 0
	global_store_dwordx4 v236, v[216:219], s[16:17]
	v_readlane_b32 s18, v232, 41
	v_readlane_b32 s19, v233, 41
	s_nop 1
	v_add_f32_e32 v231, s18, v228
	v_max_f32_e32 v228, s19, v231
	v_sub_f32_e32 v231, v231, v228
	v_sub_f32_e32 v229, s19, v228
	v_mul_f32_e32 v231, 0x3fb8aa3b, v231
	v_mul_f32_e32 v229, 0x3fb8aa3b, v229
	v_exp_f32_e32 v230, v229
	v_exp_f32_e32 v229, v231
	s_nop 0
	v_lshlrev_b32_e32 v220, 16, v200
	v_and_b32_e32 v221, 0xffff0000, v200
	v_lshlrev_b32_e32 v222, 16, v201
	v_and_b32_e32 v223, 0xffff0000, v201
	v_lshlrev_b32_e32 v224, 16, v202
	v_and_b32_e32 v225, 0xffff0000, v202
	v_lshlrev_b32_e32 v226, 16, v203
	v_and_b32_e32 v227, 0xffff0000, v203
	v_mul_f32_e32 v220, v230, v220
	v_mul_f32_e32 v221, v230, v221
	v_mul_f32_e32 v222, v230, v222
	v_mul_f32_e32 v223, v230, v223
	v_mul_f32_e32 v224, v230, v224
	v_mul_f32_e32 v225, v230, v225
	v_mul_f32_e32 v226, v230, v226
	v_mul_f32_e32 v227, v230, v227
	v_fma_f32 v0, v229, v0, v220
	v_fma_f32 v1, v229, v1, v221
	v_fma_f32 v2, v229, v2, v222
	v_fma_f32 v3, v229, v3, v223
	v_fma_f32 v4, v229, v4, v224
	v_fma_f32 v5, v229, v5, v225
	v_fma_f32 v6, v229, v6, v226
	v_fma_f32 v7, v229, v7, v227
	s_add_i32 s13, s13, s10
	s_cmp_eq_u32 s13, s11
	s_cselect_b32 s13, s8, s13
	v_cvt_pk_bf16_f32 v216, v0, v1
	v_cvt_pk_bf16_f32 v217, v2, v3
	v_cvt_pk_bf16_f32 v218, v4, v5
	v_cvt_pk_bf16_f32 v219, v6, v7
	s_lshl_b32 s14, s13, 15
	s_add_u32 s16, s66, s14
	s_addc_u32 s17, s67, 0
	global_store_dwordx4 v236, v[216:219], s[16:17]
	v_readlane_b32 s18, v232, 42
	v_readlane_b32 s19, v233, 42
	s_nop 1
	v_add_f32_e32 v231, s18, v228
	v_max_f32_e32 v228, s19, v231
	v_sub_f32_e32 v231, v231, v228
	v_sub_f32_e32 v229, s19, v228
	v_mul_f32_e32 v231, 0x3fb8aa3b, v231
	v_mul_f32_e32 v229, 0x3fb8aa3b, v229
	v_exp_f32_e32 v230, v229
	v_exp_f32_e32 v229, v231
	s_nop 0
	v_lshlrev_b32_e32 v220, 16, v204
	v_and_b32_e32 v221, 0xffff0000, v204
	v_lshlrev_b32_e32 v222, 16, v205
	v_and_b32_e32 v223, 0xffff0000, v205
	v_lshlrev_b32_e32 v224, 16, v206
	v_and_b32_e32 v225, 0xffff0000, v206
	v_lshlrev_b32_e32 v226, 16, v207
	v_and_b32_e32 v227, 0xffff0000, v207
	v_mul_f32_e32 v220, v230, v220
	v_mul_f32_e32 v221, v230, v221
	v_mul_f32_e32 v222, v230, v222
	v_mul_f32_e32 v223, v230, v223
	v_mul_f32_e32 v224, v230, v224
	v_mul_f32_e32 v225, v230, v225
	v_mul_f32_e32 v226, v230, v226
	v_mul_f32_e32 v227, v230, v227
	v_fma_f32 v0, v229, v0, v220
	v_fma_f32 v1, v229, v1, v221
	v_fma_f32 v2, v229, v2, v222
	v_fma_f32 v3, v229, v3, v223
	v_fma_f32 v4, v229, v4, v224
	v_fma_f32 v5, v229, v5, v225
	v_fma_f32 v6, v229, v6, v226
	v_fma_f32 v7, v229, v7, v227
	s_add_i32 s13, s13, s10
	s_cmp_eq_u32 s13, s11
	s_cselect_b32 s13, s8, s13
	v_cvt_pk_bf16_f32 v216, v0, v1
	v_cvt_pk_bf16_f32 v217, v2, v3
	v_cvt_pk_bf16_f32 v218, v4, v5
	v_cvt_pk_bf16_f32 v219, v6, v7
	s_lshl_b32 s14, s13, 15
	s_add_u32 s16, s66, s14
	s_addc_u32 s17, s67, 0
	global_store_dwordx4 v236, v[216:219], s[16:17]
	v_readlane_b32 s18, v232, 43
	v_readlane_b32 s19, v233, 43
	s_nop 1
	v_add_f32_e32 v231, s18, v228
	v_max_f32_e32 v228, s19, v231
	v_sub_f32_e32 v231, v231, v228
	v_sub_f32_e32 v229, s19, v228
	v_mul_f32_e32 v231, 0x3fb8aa3b, v231
	v_mul_f32_e32 v229, 0x3fb8aa3b, v229
	v_exp_f32_e32 v230, v229
	v_exp_f32_e32 v229, v231
	s_nop 0
	v_lshlrev_b32_e32 v220, 16, v208
	v_and_b32_e32 v221, 0xffff0000, v208
	v_lshlrev_b32_e32 v222, 16, v209
	v_and_b32_e32 v223, 0xffff0000, v209
	v_lshlrev_b32_e32 v224, 16, v210
	v_and_b32_e32 v225, 0xffff0000, v210
	v_lshlrev_b32_e32 v226, 16, v211
	v_and_b32_e32 v227, 0xffff0000, v211
	v_mul_f32_e32 v220, v230, v220
	v_mul_f32_e32 v221, v230, v221
	v_mul_f32_e32 v222, v230, v222
	v_mul_f32_e32 v223, v230, v223
	v_mul_f32_e32 v224, v230, v224
	v_mul_f32_e32 v225, v230, v225
	v_mul_f32_e32 v226, v230, v226
	v_mul_f32_e32 v227, v230, v227
	v_fma_f32 v0, v229, v0, v220
	v_fma_f32 v1, v229, v1, v221
	v_fma_f32 v2, v229, v2, v222
	v_fma_f32 v3, v229, v3, v223
	v_fma_f32 v4, v229, v4, v224
	v_fma_f32 v5, v229, v5, v225
	v_fma_f32 v6, v229, v6, v226
	v_fma_f32 v7, v229, v7, v227
	s_add_i32 s13, s13, s10
	s_cmp_eq_u32 s13, s11
	s_cselect_b32 s13, s8, s13
	s_waitcnt vmcnt(0)
	v_cvt_pk_bf16_f32 v216, v0, v1
	v_cvt_pk_bf16_f32 v217, v2, v3
	v_cvt_pk_bf16_f32 v218, v4, v5
	v_cvt_pk_bf16_f32 v219, v6, v7
	s_lshl_b32 s14, s13, 15
	s_add_u32 s16, s66, s14
	s_addc_u32 s17, s67, 0
	global_store_dwordx4 v236, v[216:219], s[16:17]
	v_readlane_b32 s18, v232, 44
	v_readlane_b32 s19, v233, 44
	s_nop 1
	v_add_f32_e32 v231, s18, v228
	v_max_f32_e32 v228, s19, v231
	v_sub_f32_e32 v231, v231, v228
	v_sub_f32_e32 v229, s19, v228
	v_mul_f32_e32 v231, 0x3fb8aa3b, v231
	v_mul_f32_e32 v229, 0x3fb8aa3b, v229
	v_exp_f32_e32 v230, v229
	v_exp_f32_e32 v229, v231
	s_nop 0
	v_lshlrev_b32_e32 v220, 16, v8
	v_and_b32_e32 v221, 0xffff0000, v8
	v_lshlrev_b32_e32 v222, 16, v9
	v_and_b32_e32 v223, 0xffff0000, v9
	v_lshlrev_b32_e32 v224, 16, v10
	v_and_b32_e32 v225, 0xffff0000, v10
	v_lshlrev_b32_e32 v226, 16, v11
	v_and_b32_e32 v227, 0xffff0000, v11
	v_mul_f32_e32 v220, v230, v220
	v_mul_f32_e32 v221, v230, v221
	v_mul_f32_e32 v222, v230, v222
	v_mul_f32_e32 v223, v230, v223
	v_mul_f32_e32 v224, v230, v224
	v_mul_f32_e32 v225, v230, v225
	v_mul_f32_e32 v226, v230, v226
	v_mul_f32_e32 v227, v230, v227
	v_fma_f32 v0, v229, v0, v220
	v_fma_f32 v1, v229, v1, v221
	v_fma_f32 v2, v229, v2, v222
	v_fma_f32 v3, v229, v3, v223
	v_fma_f32 v4, v229, v4, v224
	v_fma_f32 v5, v229, v5, v225
	v_fma_f32 v6, v229, v6, v226
	v_fma_f32 v7, v229, v7, v227
	s_add_i32 s13, s13, s10
	s_cmp_eq_u32 s13, s11
	s_cselect_b32 s13, s8, s13
	v_cvt_pk_bf16_f32 v216, v0, v1
	v_cvt_pk_bf16_f32 v217, v2, v3
	v_cvt_pk_bf16_f32 v218, v4, v5
	v_cvt_pk_bf16_f32 v219, v6, v7
	s_lshl_b32 s14, s13, 15
	s_add_u32 s16, s66, s14
	s_addc_u32 s17, s67, 0
	global_store_dwordx4 v236, v[216:219], s[16:17]
	v_readlane_b32 s18, v232, 45
	v_readlane_b32 s19, v233, 45
	s_nop 1
	v_add_f32_e32 v231, s18, v228
	v_max_f32_e32 v228, s19, v231
	v_sub_f32_e32 v231, v231, v228
	v_sub_f32_e32 v229, s19, v228
	v_mul_f32_e32 v231, 0x3fb8aa3b, v231
	v_mul_f32_e32 v229, 0x3fb8aa3b, v229
	v_exp_f32_e32 v230, v229
	v_exp_f32_e32 v229, v231
	s_nop 0
	v_lshlrev_b32_e32 v220, 16, v12
	v_and_b32_e32 v221, 0xffff0000, v12
	v_lshlrev_b32_e32 v222, 16, v13
	v_and_b32_e32 v223, 0xffff0000, v13
	v_lshlrev_b32_e32 v224, 16, v14
	v_and_b32_e32 v225, 0xffff0000, v14
	v_lshlrev_b32_e32 v226, 16, v15
	v_and_b32_e32 v227, 0xffff0000, v15
	v_mul_f32_e32 v220, v230, v220
	v_mul_f32_e32 v221, v230, v221
	v_mul_f32_e32 v222, v230, v222
	v_mul_f32_e32 v223, v230, v223
	v_mul_f32_e32 v224, v230, v224
	v_mul_f32_e32 v225, v230, v225
	v_mul_f32_e32 v226, v230, v226
	v_mul_f32_e32 v227, v230, v227
	v_fma_f32 v0, v229, v0, v220
	v_fma_f32 v1, v229, v1, v221
	v_fma_f32 v2, v229, v2, v222
	v_fma_f32 v3, v229, v3, v223
	v_fma_f32 v4, v229, v4, v224
	v_fma_f32 v5, v229, v5, v225
	v_fma_f32 v6, v229, v6, v226
	v_fma_f32 v7, v229, v7, v227
	s_add_i32 s13, s13, s10
	s_cmp_eq_u32 s13, s11
	s_cselect_b32 s13, s8, s13
	v_cvt_pk_bf16_f32 v216, v0, v1
	v_cvt_pk_bf16_f32 v217, v2, v3
	v_cvt_pk_bf16_f32 v218, v4, v5
	v_cvt_pk_bf16_f32 v219, v6, v7
	s_lshl_b32 s14, s13, 15
	s_add_u32 s16, s66, s14
	s_addc_u32 s17, s67, 0
	global_store_dwordx4 v236, v[216:219], s[16:17]
	v_readlane_b32 s18, v232, 46
	v_readlane_b32 s19, v233, 46
	s_nop 1
	v_add_f32_e32 v231, s18, v228
	v_max_f32_e32 v228, s19, v231
	v_sub_f32_e32 v231, v231, v228
	v_sub_f32_e32 v229, s19, v228
	v_mul_f32_e32 v231, 0x3fb8aa3b, v231
	v_mul_f32_e32 v229, 0x3fb8aa3b, v229
	v_exp_f32_e32 v230, v229
	v_exp_f32_e32 v229, v231
	s_nop 0
	v_lshlrev_b32_e32 v220, 16, v16
	v_and_b32_e32 v221, 0xffff0000, v16
	v_lshlrev_b32_e32 v222, 16, v17
	v_and_b32_e32 v223, 0xffff0000, v17
	v_lshlrev_b32_e32 v224, 16, v18
	v_and_b32_e32 v225, 0xffff0000, v18
	v_lshlrev_b32_e32 v226, 16, v19
	v_and_b32_e32 v227, 0xffff0000, v19
	v_mul_f32_e32 v220, v230, v220
	v_mul_f32_e32 v221, v230, v221
	v_mul_f32_e32 v222, v230, v222
	v_mul_f32_e32 v223, v230, v223
	v_mul_f32_e32 v224, v230, v224
	v_mul_f32_e32 v225, v230, v225
	v_mul_f32_e32 v226, v230, v226
	v_mul_f32_e32 v227, v230, v227
	v_fma_f32 v0, v229, v0, v220
	v_fma_f32 v1, v229, v1, v221
	v_fma_f32 v2, v229, v2, v222
	v_fma_f32 v3, v229, v3, v223
	v_fma_f32 v4, v229, v4, v224
	v_fma_f32 v5, v229, v5, v225
	v_fma_f32 v6, v229, v6, v226
	v_fma_f32 v7, v229, v7, v227
	s_add_i32 s13, s13, s10
	s_cmp_eq_u32 s13, s11
	s_cselect_b32 s13, s8, s13
	v_cvt_pk_bf16_f32 v216, v0, v1
	v_cvt_pk_bf16_f32 v217, v2, v3
	v_cvt_pk_bf16_f32 v218, v4, v5
	v_cvt_pk_bf16_f32 v219, v6, v7
	s_lshl_b32 s14, s13, 15
	s_add_u32 s16, s66, s14
	s_addc_u32 s17, s67, 0
	global_store_dwordx4 v236, v[216:219], s[16:17]
	v_readlane_b32 s18, v232, 47
	v_readlane_b32 s19, v233, 47
	s_nop 1
	v_add_f32_e32 v231, s18, v228
	v_max_f32_e32 v228, s19, v231
	v_sub_f32_e32 v231, v231, v228
	v_sub_f32_e32 v229, s19, v228
	v_mul_f32_e32 v231, 0x3fb8aa3b, v231
	v_mul_f32_e32 v229, 0x3fb8aa3b, v229
	v_exp_f32_e32 v230, v229
	v_exp_f32_e32 v229, v231
	s_nop 0
	v_lshlrev_b32_e32 v220, 16, v20
	v_and_b32_e32 v221, 0xffff0000, v20
	v_lshlrev_b32_e32 v222, 16, v21
	v_and_b32_e32 v223, 0xffff0000, v21
	v_lshlrev_b32_e32 v224, 16, v22
	v_and_b32_e32 v225, 0xffff0000, v22
	v_lshlrev_b32_e32 v226, 16, v23
	v_and_b32_e32 v227, 0xffff0000, v23
	v_mul_f32_e32 v220, v230, v220
	v_mul_f32_e32 v221, v230, v221
	v_mul_f32_e32 v222, v230, v222
	v_mul_f32_e32 v223, v230, v223
	v_mul_f32_e32 v224, v230, v224
	v_mul_f32_e32 v225, v230, v225
	v_mul_f32_e32 v226, v230, v226
	v_mul_f32_e32 v227, v230, v227
	v_fma_f32 v0, v229, v0, v220
	v_fma_f32 v1, v229, v1, v221
	v_fma_f32 v2, v229, v2, v222
	v_fma_f32 v3, v229, v3, v223
	v_fma_f32 v4, v229, v4, v224
	v_fma_f32 v5, v229, v5, v225
	v_fma_f32 v6, v229, v6, v226
	v_fma_f32 v7, v229, v7, v227
	s_add_i32 s13, s13, s10
	s_cmp_eq_u32 s13, s11
	s_cselect_b32 s13, s8, s13
	v_cvt_pk_bf16_f32 v216, v0, v1
	v_cvt_pk_bf16_f32 v217, v2, v3
	v_cvt_pk_bf16_f32 v218, v4, v5
	v_cvt_pk_bf16_f32 v219, v6, v7
	s_lshl_b32 s14, s13, 15
	s_add_u32 s16, s66, s14
	s_addc_u32 s17, s67, 0
	global_store_dwordx4 v236, v[216:219], s[16:17]
	v_readlane_b32 s18, v232, 48
	v_readlane_b32 s19, v233, 48
	s_nop 1
	v_add_f32_e32 v231, s18, v228
	v_max_f32_e32 v228, s19, v231
	v_sub_f32_e32 v231, v231, v228
	v_sub_f32_e32 v229, s19, v228
	v_mul_f32_e32 v231, 0x3fb8aa3b, v231
	v_mul_f32_e32 v229, 0x3fb8aa3b, v229
	v_exp_f32_e32 v230, v229
	v_exp_f32_e32 v229, v231
	s_nop 0
	v_lshlrev_b32_e32 v220, 16, v24
	v_and_b32_e32 v221, 0xffff0000, v24
	v_lshlrev_b32_e32 v222, 16, v25
	v_and_b32_e32 v223, 0xffff0000, v25
	v_lshlrev_b32_e32 v224, 16, v26
	v_and_b32_e32 v225, 0xffff0000, v26
	v_lshlrev_b32_e32 v226, 16, v27
	v_and_b32_e32 v227, 0xffff0000, v27
	v_mul_f32_e32 v220, v230, v220
	v_mul_f32_e32 v221, v230, v221
	v_mul_f32_e32 v222, v230, v222
	v_mul_f32_e32 v223, v230, v223
	v_mul_f32_e32 v224, v230, v224
	v_mul_f32_e32 v225, v230, v225
	v_mul_f32_e32 v226, v230, v226
	v_mul_f32_e32 v227, v230, v227
	v_fma_f32 v0, v229, v0, v220
	v_fma_f32 v1, v229, v1, v221
	v_fma_f32 v2, v229, v2, v222
	v_fma_f32 v3, v229, v3, v223
	v_fma_f32 v4, v229, v4, v224
	v_fma_f32 v5, v229, v5, v225
	v_fma_f32 v6, v229, v6, v226
	v_fma_f32 v7, v229, v7, v227
	s_add_i32 s13, s13, s10
	s_cmp_eq_u32 s13, s11
	s_cselect_b32 s13, s8, s13
	v_cvt_pk_bf16_f32 v216, v0, v1
	v_cvt_pk_bf16_f32 v217, v2, v3
	v_cvt_pk_bf16_f32 v218, v4, v5
	v_cvt_pk_bf16_f32 v219, v6, v7
	s_lshl_b32 s14, s13, 15
	s_add_u32 s16, s66, s14
	s_addc_u32 s17, s67, 0
	global_store_dwordx4 v236, v[216:219], s[16:17]
	v_readlane_b32 s18, v232, 49
	v_readlane_b32 s19, v233, 49
	s_nop 1
	v_add_f32_e32 v231, s18, v228
	v_max_f32_e32 v228, s19, v231
	v_sub_f32_e32 v231, v231, v228
	v_sub_f32_e32 v229, s19, v228
	v_mul_f32_e32 v231, 0x3fb8aa3b, v231
	v_mul_f32_e32 v229, 0x3fb8aa3b, v229
	v_exp_f32_e32 v230, v229
	v_exp_f32_e32 v229, v231
	s_nop 0
	v_lshlrev_b32_e32 v220, 16, v28
	v_and_b32_e32 v221, 0xffff0000, v28
	v_lshlrev_b32_e32 v222, 16, v29
	v_and_b32_e32 v223, 0xffff0000, v29
	v_lshlrev_b32_e32 v224, 16, v30
	v_and_b32_e32 v225, 0xffff0000, v30
	v_lshlrev_b32_e32 v226, 16, v31
	v_and_b32_e32 v227, 0xffff0000, v31
	v_mul_f32_e32 v220, v230, v220
	v_mul_f32_e32 v221, v230, v221
	v_mul_f32_e32 v222, v230, v222
	v_mul_f32_e32 v223, v230, v223
	v_mul_f32_e32 v224, v230, v224
	v_mul_f32_e32 v225, v230, v225
	v_mul_f32_e32 v226, v230, v226
	v_mul_f32_e32 v227, v230, v227
	v_fma_f32 v0, v229, v0, v220
	v_fma_f32 v1, v229, v1, v221
	v_fma_f32 v2, v229, v2, v222
	v_fma_f32 v3, v229, v3, v223
	v_fma_f32 v4, v229, v4, v224
	v_fma_f32 v5, v229, v5, v225
	v_fma_f32 v6, v229, v6, v226
	v_fma_f32 v7, v229, v7, v227
	s_add_i32 s13, s13, s10
	s_cmp_eq_u32 s13, s11
	s_cselect_b32 s13, s8, s13
	v_cvt_pk_bf16_f32 v216, v0, v1
	v_cvt_pk_bf16_f32 v217, v2, v3
	v_cvt_pk_bf16_f32 v218, v4, v5
	v_cvt_pk_bf16_f32 v219, v6, v7
	s_lshl_b32 s14, s13, 15
	s_add_u32 s16, s66, s14
	s_addc_u32 s17, s67, 0
	global_store_dwordx4 v236, v[216:219], s[16:17]
	v_readlane_b32 s18, v232, 50
	v_readlane_b32 s19, v233, 50
	s_nop 1
	v_add_f32_e32 v231, s18, v228
	v_max_f32_e32 v228, s19, v231
	v_sub_f32_e32 v231, v231, v228
	v_sub_f32_e32 v229, s19, v228
	v_mul_f32_e32 v231, 0x3fb8aa3b, v231
	v_mul_f32_e32 v229, 0x3fb8aa3b, v229
	v_exp_f32_e32 v230, v229
	v_exp_f32_e32 v229, v231
	s_nop 0
	v_lshlrev_b32_e32 v220, 16, v32
	v_and_b32_e32 v221, 0xffff0000, v32
	v_lshlrev_b32_e32 v222, 16, v33
	v_and_b32_e32 v223, 0xffff0000, v33
	v_lshlrev_b32_e32 v224, 16, v34
	v_and_b32_e32 v225, 0xffff0000, v34
	v_lshlrev_b32_e32 v226, 16, v35
	v_and_b32_e32 v227, 0xffff0000, v35
	v_mul_f32_e32 v220, v230, v220
	v_mul_f32_e32 v221, v230, v221
	v_mul_f32_e32 v222, v230, v222
	v_mul_f32_e32 v223, v230, v223
	v_mul_f32_e32 v224, v230, v224
	v_mul_f32_e32 v225, v230, v225
	v_mul_f32_e32 v226, v230, v226
	v_mul_f32_e32 v227, v230, v227
	v_fma_f32 v0, v229, v0, v220
	v_fma_f32 v1, v229, v1, v221
	v_fma_f32 v2, v229, v2, v222
	v_fma_f32 v3, v229, v3, v223
	v_fma_f32 v4, v229, v4, v224
	v_fma_f32 v5, v229, v5, v225
	v_fma_f32 v6, v229, v6, v226
	v_fma_f32 v7, v229, v7, v227
	s_add_i32 s13, s13, s10
	s_cmp_eq_u32 s13, s11
	s_cselect_b32 s13, s8, s13
	v_cvt_pk_bf16_f32 v216, v0, v1
	v_cvt_pk_bf16_f32 v217, v2, v3
	v_cvt_pk_bf16_f32 v218, v4, v5
	v_cvt_pk_bf16_f32 v219, v6, v7
	s_lshl_b32 s14, s13, 15
	s_add_u32 s16, s66, s14
	s_addc_u32 s17, s67, 0
	global_store_dwordx4 v236, v[216:219], s[16:17]
	v_readlane_b32 s18, v232, 51
	v_readlane_b32 s19, v233, 51
	s_nop 1
	v_add_f32_e32 v231, s18, v228
	v_max_f32_e32 v228, s19, v231
	v_sub_f32_e32 v231, v231, v228
	v_sub_f32_e32 v229, s19, v228
	v_mul_f32_e32 v231, 0x3fb8aa3b, v231
	v_mul_f32_e32 v229, 0x3fb8aa3b, v229
	v_exp_f32_e32 v230, v229
	v_exp_f32_e32 v229, v231
	s_nop 0
	v_lshlrev_b32_e32 v220, 16, v36
	v_and_b32_e32 v221, 0xffff0000, v36
	v_lshlrev_b32_e32 v222, 16, v37
	v_and_b32_e32 v223, 0xffff0000, v37
	v_lshlrev_b32_e32 v224, 16, v38
	v_and_b32_e32 v225, 0xffff0000, v38
	v_lshlrev_b32_e32 v226, 16, v39
	v_and_b32_e32 v227, 0xffff0000, v39
	v_mul_f32_e32 v220, v230, v220
	v_mul_f32_e32 v221, v230, v221
	v_mul_f32_e32 v222, v230, v222
	v_mul_f32_e32 v223, v230, v223
	v_mul_f32_e32 v224, v230, v224
	v_mul_f32_e32 v225, v230, v225
	v_mul_f32_e32 v226, v230, v226
	v_mul_f32_e32 v227, v230, v227
	v_fma_f32 v0, v229, v0, v220
	v_fma_f32 v1, v229, v1, v221
	v_fma_f32 v2, v229, v2, v222
	v_fma_f32 v3, v229, v3, v223
	v_fma_f32 v4, v229, v4, v224
	v_fma_f32 v5, v229, v5, v225
	v_fma_f32 v6, v229, v6, v226
	v_fma_f32 v7, v229, v7, v227
	s_add_i32 s13, s13, s10
	s_cmp_eq_u32 s13, s11
	s_cselect_b32 s13, s8, s13
	v_cvt_pk_bf16_f32 v216, v0, v1
	v_cvt_pk_bf16_f32 v217, v2, v3
	v_cvt_pk_bf16_f32 v218, v4, v5
	v_cvt_pk_bf16_f32 v219, v6, v7
	s_lshl_b32 s14, s13, 15
	s_add_u32 s16, s66, s14
	s_addc_u32 s17, s67, 0
	global_store_dwordx4 v236, v[216:219], s[16:17]
	v_readlane_b32 s18, v232, 52
	v_readlane_b32 s19, v233, 52
	s_nop 1
	v_add_f32_e32 v231, s18, v228
	v_max_f32_e32 v228, s19, v231
	v_sub_f32_e32 v231, v231, v228
	v_sub_f32_e32 v229, s19, v228
	v_mul_f32_e32 v231, 0x3fb8aa3b, v231
	v_mul_f32_e32 v229, 0x3fb8aa3b, v229
	v_exp_f32_e32 v230, v229
	v_exp_f32_e32 v229, v231
	s_nop 0
	v_lshlrev_b32_e32 v220, 16, v40
	v_and_b32_e32 v221, 0xffff0000, v40
	v_lshlrev_b32_e32 v222, 16, v41
	v_and_b32_e32 v223, 0xffff0000, v41
	v_lshlrev_b32_e32 v224, 16, v42
	v_and_b32_e32 v225, 0xffff0000, v42
	v_lshlrev_b32_e32 v226, 16, v43
	v_and_b32_e32 v227, 0xffff0000, v43
	v_mul_f32_e32 v220, v230, v220
	v_mul_f32_e32 v221, v230, v221
	v_mul_f32_e32 v222, v230, v222
	v_mul_f32_e32 v223, v230, v223
	v_mul_f32_e32 v224, v230, v224
	v_mul_f32_e32 v225, v230, v225
	v_mul_f32_e32 v226, v230, v226
	v_mul_f32_e32 v227, v230, v227
	v_fma_f32 v0, v229, v0, v220
	v_fma_f32 v1, v229, v1, v221
	v_fma_f32 v2, v229, v2, v222
	v_fma_f32 v3, v229, v3, v223
	v_fma_f32 v4, v229, v4, v224
	v_fma_f32 v5, v229, v5, v225
	v_fma_f32 v6, v229, v6, v226
	v_fma_f32 v7, v229, v7, v227
	s_add_i32 s13, s13, s10
	s_cmp_eq_u32 s13, s11
	s_cselect_b32 s13, s8, s13
	v_cvt_pk_bf16_f32 v216, v0, v1
	v_cvt_pk_bf16_f32 v217, v2, v3
	v_cvt_pk_bf16_f32 v218, v4, v5
	v_cvt_pk_bf16_f32 v219, v6, v7
	s_lshl_b32 s14, s13, 15
	s_add_u32 s16, s66, s14
	s_addc_u32 s17, s67, 0
	global_store_dwordx4 v236, v[216:219], s[16:17]
	v_readlane_b32 s18, v232, 53
	v_readlane_b32 s19, v233, 53
	s_nop 1
	v_add_f32_e32 v231, s18, v228
	v_max_f32_e32 v228, s19, v231
	v_sub_f32_e32 v231, v231, v228
	v_sub_f32_e32 v229, s19, v228
	v_mul_f32_e32 v231, 0x3fb8aa3b, v231
	v_mul_f32_e32 v229, 0x3fb8aa3b, v229
	v_exp_f32_e32 v230, v229
	v_exp_f32_e32 v229, v231
	s_nop 0
	v_lshlrev_b32_e32 v220, 16, v44
	v_and_b32_e32 v221, 0xffff0000, v44
	v_lshlrev_b32_e32 v222, 16, v45
	v_and_b32_e32 v223, 0xffff0000, v45
	v_lshlrev_b32_e32 v224, 16, v46
	v_and_b32_e32 v225, 0xffff0000, v46
	v_lshlrev_b32_e32 v226, 16, v47
	v_and_b32_e32 v227, 0xffff0000, v47
	v_mul_f32_e32 v220, v230, v220
	v_mul_f32_e32 v221, v230, v221
	v_mul_f32_e32 v222, v230, v222
	v_mul_f32_e32 v223, v230, v223
	v_mul_f32_e32 v224, v230, v224
	v_mul_f32_e32 v225, v230, v225
	v_mul_f32_e32 v226, v230, v226
	v_mul_f32_e32 v227, v230, v227
	v_fma_f32 v0, v229, v0, v220
	v_fma_f32 v1, v229, v1, v221
	v_fma_f32 v2, v229, v2, v222
	v_fma_f32 v3, v229, v3, v223
	v_fma_f32 v4, v229, v4, v224
	v_fma_f32 v5, v229, v5, v225
	v_fma_f32 v6, v229, v6, v226
	v_fma_f32 v7, v229, v7, v227
	s_add_i32 s13, s13, s10
	s_cmp_eq_u32 s13, s11
	s_cselect_b32 s13, s8, s13
	v_cvt_pk_bf16_f32 v216, v0, v1
	v_cvt_pk_bf16_f32 v217, v2, v3
	v_cvt_pk_bf16_f32 v218, v4, v5
	v_cvt_pk_bf16_f32 v219, v6, v7
	s_lshl_b32 s14, s13, 15
	s_add_u32 s16, s66, s14
	s_addc_u32 s17, s67, 0
	global_store_dwordx4 v236, v[216:219], s[16:17]
	v_readlane_b32 s18, v232, 54
	v_readlane_b32 s19, v233, 54
	s_nop 1
	v_add_f32_e32 v231, s18, v228
	v_max_f32_e32 v228, s19, v231
	v_sub_f32_e32 v231, v231, v228
	v_sub_f32_e32 v229, s19, v228
	v_mul_f32_e32 v231, 0x3fb8aa3b, v231
	v_mul_f32_e32 v229, 0x3fb8aa3b, v229
	v_exp_f32_e32 v230, v229
	v_exp_f32_e32 v229, v231
	s_nop 0
	v_lshlrev_b32_e32 v220, 16, v48
	v_and_b32_e32 v221, 0xffff0000, v48
	v_lshlrev_b32_e32 v222, 16, v49
	v_and_b32_e32 v223, 0xffff0000, v49
	v_lshlrev_b32_e32 v224, 16, v50
	v_and_b32_e32 v225, 0xffff0000, v50
	v_lshlrev_b32_e32 v226, 16, v51
	v_and_b32_e32 v227, 0xffff0000, v51
	v_mul_f32_e32 v220, v230, v220
	v_mul_f32_e32 v221, v230, v221
	v_mul_f32_e32 v222, v230, v222
	v_mul_f32_e32 v223, v230, v223
	v_mul_f32_e32 v224, v230, v224
	v_mul_f32_e32 v225, v230, v225
	v_mul_f32_e32 v226, v230, v226
	v_mul_f32_e32 v227, v230, v227
	v_fma_f32 v0, v229, v0, v220
	v_fma_f32 v1, v229, v1, v221
	v_fma_f32 v2, v229, v2, v222
	v_fma_f32 v3, v229, v3, v223
	v_fma_f32 v4, v229, v4, v224
	v_fma_f32 v5, v229, v5, v225
	v_fma_f32 v6, v229, v6, v226
	v_fma_f32 v7, v229, v7, v227
	s_add_i32 s13, s13, s10
	s_cmp_eq_u32 s13, s11
	s_cselect_b32 s13, s8, s13
	v_cvt_pk_bf16_f32 v216, v0, v1
	v_cvt_pk_bf16_f32 v217, v2, v3
	v_cvt_pk_bf16_f32 v218, v4, v5
	v_cvt_pk_bf16_f32 v219, v6, v7
	s_lshl_b32 s14, s13, 15
	s_add_u32 s16, s66, s14
	s_addc_u32 s17, s67, 0
	global_store_dwordx4 v236, v[216:219], s[16:17]
	v_readlane_b32 s18, v232, 55
	v_readlane_b32 s19, v233, 55
	s_nop 1
	v_add_f32_e32 v231, s18, v228
	v_max_f32_e32 v228, s19, v231
	v_sub_f32_e32 v231, v231, v228
	v_sub_f32_e32 v229, s19, v228
	v_mul_f32_e32 v231, 0x3fb8aa3b, v231
	v_mul_f32_e32 v229, 0x3fb8aa3b, v229
	v_exp_f32_e32 v230, v229
	v_exp_f32_e32 v229, v231
	s_nop 0
	v_lshlrev_b32_e32 v220, 16, v52
	v_and_b32_e32 v221, 0xffff0000, v52
	v_lshlrev_b32_e32 v222, 16, v53
	v_and_b32_e32 v223, 0xffff0000, v53
	v_lshlrev_b32_e32 v224, 16, v54
	v_and_b32_e32 v225, 0xffff0000, v54
	v_lshlrev_b32_e32 v226, 16, v55
	v_and_b32_e32 v227, 0xffff0000, v55
	v_mul_f32_e32 v220, v230, v220
	v_mul_f32_e32 v221, v230, v221
	v_mul_f32_e32 v222, v230, v222
	v_mul_f32_e32 v223, v230, v223
	v_mul_f32_e32 v224, v230, v224
	v_mul_f32_e32 v225, v230, v225
	v_mul_f32_e32 v226, v230, v226
	v_mul_f32_e32 v227, v230, v227
	v_fma_f32 v0, v229, v0, v220
	v_fma_f32 v1, v229, v1, v221
	v_fma_f32 v2, v229, v2, v222
	v_fma_f32 v3, v229, v3, v223
	v_fma_f32 v4, v229, v4, v224
	v_fma_f32 v5, v229, v5, v225
	v_fma_f32 v6, v229, v6, v226
	v_fma_f32 v7, v229, v7, v227
	s_add_i32 s13, s13, s10
	s_cmp_eq_u32 s13, s11
	s_cselect_b32 s13, s8, s13
	v_cvt_pk_bf16_f32 v216, v0, v1
	v_cvt_pk_bf16_f32 v217, v2, v3
	v_cvt_pk_bf16_f32 v218, v4, v5
	v_cvt_pk_bf16_f32 v219, v6, v7
	s_lshl_b32 s14, s13, 15
	s_add_u32 s16, s66, s14
	s_addc_u32 s17, s67, 0
	global_store_dwordx4 v236, v[216:219], s[16:17]
	v_readlane_b32 s18, v232, 56
	v_readlane_b32 s19, v233, 56
	s_nop 1
	v_add_f32_e32 v231, s18, v228
	v_max_f32_e32 v228, s19, v231
	v_sub_f32_e32 v231, v231, v228
	v_sub_f32_e32 v229, s19, v228
	v_mul_f32_e32 v231, 0x3fb8aa3b, v231
	v_mul_f32_e32 v229, 0x3fb8aa3b, v229
	v_exp_f32_e32 v230, v229
	v_exp_f32_e32 v229, v231
	s_nop 0
	v_lshlrev_b32_e32 v220, 16, v56
	v_and_b32_e32 v221, 0xffff0000, v56
	v_lshlrev_b32_e32 v222, 16, v57
	v_and_b32_e32 v223, 0xffff0000, v57
	v_lshlrev_b32_e32 v224, 16, v58
	v_and_b32_e32 v225, 0xffff0000, v58
	v_lshlrev_b32_e32 v226, 16, v59
	v_and_b32_e32 v227, 0xffff0000, v59
	v_mul_f32_e32 v220, v230, v220
	v_mul_f32_e32 v221, v230, v221
	v_mul_f32_e32 v222, v230, v222
	v_mul_f32_e32 v223, v230, v223
	v_mul_f32_e32 v224, v230, v224
	v_mul_f32_e32 v225, v230, v225
	v_mul_f32_e32 v226, v230, v226
	v_mul_f32_e32 v227, v230, v227
	v_fma_f32 v0, v229, v0, v220
	v_fma_f32 v1, v229, v1, v221
	v_fma_f32 v2, v229, v2, v222
	v_fma_f32 v3, v229, v3, v223
	v_fma_f32 v4, v229, v4, v224
	v_fma_f32 v5, v229, v5, v225
	v_fma_f32 v6, v229, v6, v226
	v_fma_f32 v7, v229, v7, v227
	s_add_i32 s13, s13, s10
	s_cmp_eq_u32 s13, s11
	s_cselect_b32 s13, s8, s13
	v_cvt_pk_bf16_f32 v216, v0, v1
	v_cvt_pk_bf16_f32 v217, v2, v3
	v_cvt_pk_bf16_f32 v218, v4, v5
	v_cvt_pk_bf16_f32 v219, v6, v7
	s_lshl_b32 s14, s13, 15
	s_add_u32 s16, s66, s14
	s_addc_u32 s17, s67, 0
	global_store_dwordx4 v236, v[216:219], s[16:17]
	v_readlane_b32 s18, v232, 57
	v_readlane_b32 s19, v233, 57
	s_nop 1
	v_add_f32_e32 v231, s18, v228
	v_max_f32_e32 v228, s19, v231
	v_sub_f32_e32 v231, v231, v228
	v_sub_f32_e32 v229, s19, v228
	v_mul_f32_e32 v231, 0x3fb8aa3b, v231
	v_mul_f32_e32 v229, 0x3fb8aa3b, v229
	v_exp_f32_e32 v230, v229
	v_exp_f32_e32 v229, v231
	s_nop 0
	v_lshlrev_b32_e32 v220, 16, v60
	v_and_b32_e32 v221, 0xffff0000, v60
	v_lshlrev_b32_e32 v222, 16, v61
	v_and_b32_e32 v223, 0xffff0000, v61
	v_lshlrev_b32_e32 v224, 16, v62
	v_and_b32_e32 v225, 0xffff0000, v62
	v_lshlrev_b32_e32 v226, 16, v63
	v_and_b32_e32 v227, 0xffff0000, v63
	v_mul_f32_e32 v220, v230, v220
	v_mul_f32_e32 v221, v230, v221
	v_mul_f32_e32 v222, v230, v222
	v_mul_f32_e32 v223, v230, v223
	v_mul_f32_e32 v224, v230, v224
	v_mul_f32_e32 v225, v230, v225
	v_mul_f32_e32 v226, v230, v226
	v_mul_f32_e32 v227, v230, v227
	v_fma_f32 v0, v229, v0, v220
	v_fma_f32 v1, v229, v1, v221
	v_fma_f32 v2, v229, v2, v222
	v_fma_f32 v3, v229, v3, v223
	v_fma_f32 v4, v229, v4, v224
	v_fma_f32 v5, v229, v5, v225
	v_fma_f32 v6, v229, v6, v226
	v_fma_f32 v7, v229, v7, v227
	s_add_i32 s13, s13, s10
	s_cmp_eq_u32 s13, s11
	s_cselect_b32 s13, s8, s13
	v_cvt_pk_bf16_f32 v216, v0, v1
	v_cvt_pk_bf16_f32 v217, v2, v3
	v_cvt_pk_bf16_f32 v218, v4, v5
	v_cvt_pk_bf16_f32 v219, v6, v7
	s_lshl_b32 s14, s13, 15
	s_add_u32 s16, s66, s14
	s_addc_u32 s17, s67, 0
	global_store_dwordx4 v236, v[216:219], s[16:17]
	v_readlane_b32 s18, v232, 58
	v_readlane_b32 s19, v233, 58
	s_nop 1
	v_add_f32_e32 v231, s18, v228
	v_max_f32_e32 v228, s19, v231
	v_sub_f32_e32 v231, v231, v228
	v_sub_f32_e32 v229, s19, v228
	v_mul_f32_e32 v231, 0x3fb8aa3b, v231
	v_mul_f32_e32 v229, 0x3fb8aa3b, v229
	v_exp_f32_e32 v230, v229
	v_exp_f32_e32 v229, v231
	s_nop 0
	v_lshlrev_b32_e32 v220, 16, v64
	v_and_b32_e32 v221, 0xffff0000, v64
	v_lshlrev_b32_e32 v222, 16, v65
	v_and_b32_e32 v223, 0xffff0000, v65
	v_lshlrev_b32_e32 v224, 16, v66
	v_and_b32_e32 v225, 0xffff0000, v66
	v_lshlrev_b32_e32 v226, 16, v67
	v_and_b32_e32 v227, 0xffff0000, v67
	v_mul_f32_e32 v220, v230, v220
	v_mul_f32_e32 v221, v230, v221
	v_mul_f32_e32 v222, v230, v222
	v_mul_f32_e32 v223, v230, v223
	v_mul_f32_e32 v224, v230, v224
	v_mul_f32_e32 v225, v230, v225
	v_mul_f32_e32 v226, v230, v226
	v_mul_f32_e32 v227, v230, v227
	v_fma_f32 v0, v229, v0, v220
	v_fma_f32 v1, v229, v1, v221
	v_fma_f32 v2, v229, v2, v222
	v_fma_f32 v3, v229, v3, v223
	v_fma_f32 v4, v229, v4, v224
	v_fma_f32 v5, v229, v5, v225
	v_fma_f32 v6, v229, v6, v226
	v_fma_f32 v7, v229, v7, v227
	s_add_i32 s13, s13, s10
	s_cmp_eq_u32 s13, s11
	s_cselect_b32 s13, s8, s13
	v_cvt_pk_bf16_f32 v216, v0, v1
	v_cvt_pk_bf16_f32 v217, v2, v3
	v_cvt_pk_bf16_f32 v218, v4, v5
	v_cvt_pk_bf16_f32 v219, v6, v7
	s_lshl_b32 s14, s13, 15
	s_add_u32 s16, s66, s14
	s_addc_u32 s17, s67, 0
	global_store_dwordx4 v236, v[216:219], s[16:17]
	v_readlane_b32 s18, v232, 59
	v_readlane_b32 s19, v233, 59
	s_nop 1
	v_add_f32_e32 v231, s18, v228
	v_max_f32_e32 v228, s19, v231
	v_sub_f32_e32 v231, v231, v228
	v_sub_f32_e32 v229, s19, v228
	v_mul_f32_e32 v231, 0x3fb8aa3b, v231
	v_mul_f32_e32 v229, 0x3fb8aa3b, v229
	v_exp_f32_e32 v230, v229
	v_exp_f32_e32 v229, v231
	s_nop 0
	v_lshlrev_b32_e32 v220, 16, v68
	v_and_b32_e32 v221, 0xffff0000, v68
	v_lshlrev_b32_e32 v222, 16, v69
	v_and_b32_e32 v223, 0xffff0000, v69
	v_lshlrev_b32_e32 v224, 16, v70
	v_and_b32_e32 v225, 0xffff0000, v70
	v_lshlrev_b32_e32 v226, 16, v71
	v_and_b32_e32 v227, 0xffff0000, v71
	v_mul_f32_e32 v220, v230, v220
	v_mul_f32_e32 v221, v230, v221
	v_mul_f32_e32 v222, v230, v222
	v_mul_f32_e32 v223, v230, v223
	v_mul_f32_e32 v224, v230, v224
	v_mul_f32_e32 v225, v230, v225
	v_mul_f32_e32 v226, v230, v226
	v_mul_f32_e32 v227, v230, v227
	v_fma_f32 v0, v229, v0, v220
	v_fma_f32 v1, v229, v1, v221
	v_fma_f32 v2, v229, v2, v222
	v_fma_f32 v3, v229, v3, v223
	v_fma_f32 v4, v229, v4, v224
	v_fma_f32 v5, v229, v5, v225
	v_fma_f32 v6, v229, v6, v226
	v_fma_f32 v7, v229, v7, v227
	s_add_i32 s13, s13, s10
	s_cmp_eq_u32 s13, s11
	s_cselect_b32 s13, s8, s13
	v_cvt_pk_bf16_f32 v216, v0, v1
	v_cvt_pk_bf16_f32 v217, v2, v3
	v_cvt_pk_bf16_f32 v218, v4, v5
	v_cvt_pk_bf16_f32 v219, v6, v7
	s_lshl_b32 s14, s13, 15
	s_add_u32 s16, s66, s14
	s_addc_u32 s17, s67, 0
	global_store_dwordx4 v236, v[216:219], s[16:17]
	v_readlane_b32 s18, v232, 60
	v_readlane_b32 s19, v233, 60
	s_nop 1
	v_add_f32_e32 v231, s18, v228
	v_max_f32_e32 v228, s19, v231
	v_sub_f32_e32 v231, v231, v228
	v_sub_f32_e32 v229, s19, v228
	v_mul_f32_e32 v231, 0x3fb8aa3b, v231
	v_mul_f32_e32 v229, 0x3fb8aa3b, v229
	v_exp_f32_e32 v230, v229
	v_exp_f32_e32 v229, v231
	s_nop 0
	v_lshlrev_b32_e32 v220, 16, v72
	v_and_b32_e32 v221, 0xffff0000, v72
	v_lshlrev_b32_e32 v222, 16, v73
	v_and_b32_e32 v223, 0xffff0000, v73
	v_lshlrev_b32_e32 v224, 16, v74
	v_and_b32_e32 v225, 0xffff0000, v74
	v_lshlrev_b32_e32 v226, 16, v75
	v_and_b32_e32 v227, 0xffff0000, v75
	v_mul_f32_e32 v220, v230, v220
	v_mul_f32_e32 v221, v230, v221
	v_mul_f32_e32 v222, v230, v222
	v_mul_f32_e32 v223, v230, v223
	v_mul_f32_e32 v224, v230, v224
	v_mul_f32_e32 v225, v230, v225
	v_mul_f32_e32 v226, v230, v226
	v_mul_f32_e32 v227, v230, v227
	v_fma_f32 v0, v229, v0, v220
	v_fma_f32 v1, v229, v1, v221
	v_fma_f32 v2, v229, v2, v222
	v_fma_f32 v3, v229, v3, v223
	v_fma_f32 v4, v229, v4, v224
	v_fma_f32 v5, v229, v5, v225
	v_fma_f32 v6, v229, v6, v226
	v_fma_f32 v7, v229, v7, v227
	s_add_i32 s13, s13, s10
	s_cmp_eq_u32 s13, s11
	s_cselect_b32 s13, s8, s13
	v_cvt_pk_bf16_f32 v216, v0, v1
	v_cvt_pk_bf16_f32 v217, v2, v3
	v_cvt_pk_bf16_f32 v218, v4, v5
	v_cvt_pk_bf16_f32 v219, v6, v7
	s_lshl_b32 s14, s13, 15
	s_add_u32 s16, s66, s14
	s_addc_u32 s17, s67, 0
	global_store_dwordx4 v236, v[216:219], s[16:17]
	v_readlane_b32 s18, v232, 61
	v_readlane_b32 s19, v233, 61
	s_nop 1
	v_add_f32_e32 v231, s18, v228
	v_max_f32_e32 v228, s19, v231
	v_sub_f32_e32 v231, v231, v228
	v_sub_f32_e32 v229, s19, v228
	v_mul_f32_e32 v231, 0x3fb8aa3b, v231
	v_mul_f32_e32 v229, 0x3fb8aa3b, v229
	v_exp_f32_e32 v230, v229
	v_exp_f32_e32 v229, v231
	s_nop 0
	v_lshlrev_b32_e32 v220, 16, v76
	v_and_b32_e32 v221, 0xffff0000, v76
	v_lshlrev_b32_e32 v222, 16, v77
	v_and_b32_e32 v223, 0xffff0000, v77
	v_lshlrev_b32_e32 v224, 16, v78
	v_and_b32_e32 v225, 0xffff0000, v78
	v_lshlrev_b32_e32 v226, 16, v79
	v_and_b32_e32 v227, 0xffff0000, v79
	v_mul_f32_e32 v220, v230, v220
	v_mul_f32_e32 v221, v230, v221
	v_mul_f32_e32 v222, v230, v222
	v_mul_f32_e32 v223, v230, v223
	v_mul_f32_e32 v224, v230, v224
	v_mul_f32_e32 v225, v230, v225
	v_mul_f32_e32 v226, v230, v226
	v_mul_f32_e32 v227, v230, v227
	v_fma_f32 v0, v229, v0, v220
	v_fma_f32 v1, v229, v1, v221
	v_fma_f32 v2, v229, v2, v222
	v_fma_f32 v3, v229, v3, v223
	v_fma_f32 v4, v229, v4, v224
	v_fma_f32 v5, v229, v5, v225
	v_fma_f32 v6, v229, v6, v226
	v_fma_f32 v7, v229, v7, v227
	s_add_i32 s13, s13, s10
	s_cmp_eq_u32 s13, s11
	s_cselect_b32 s13, s8, s13
	v_cvt_pk_bf16_f32 v216, v0, v1
	v_cvt_pk_bf16_f32 v217, v2, v3
	v_cvt_pk_bf16_f32 v218, v4, v5
	v_cvt_pk_bf16_f32 v219, v6, v7
	s_lshl_b32 s14, s13, 15
	s_add_u32 s16, s66, s14
	s_addc_u32 s17, s67, 0
	global_store_dwordx4 v236, v[216:219], s[16:17]
	v_readlane_b32 s18, v232, 62
	v_readlane_b32 s19, v233, 62
	s_nop 1
	v_add_f32_e32 v231, s18, v228
	v_max_f32_e32 v228, s19, v231
	v_sub_f32_e32 v231, v231, v228
	v_sub_f32_e32 v229, s19, v228
	v_mul_f32_e32 v231, 0x3fb8aa3b, v231
	v_mul_f32_e32 v229, 0x3fb8aa3b, v229
	v_exp_f32_e32 v230, v229
	v_exp_f32_e32 v229, v231
	s_nop 0
	v_lshlrev_b32_e32 v220, 16, v80
	v_and_b32_e32 v221, 0xffff0000, v80
	v_lshlrev_b32_e32 v222, 16, v81
	v_and_b32_e32 v223, 0xffff0000, v81
	v_lshlrev_b32_e32 v224, 16, v82
	v_and_b32_e32 v225, 0xffff0000, v82
	v_lshlrev_b32_e32 v226, 16, v83
	v_and_b32_e32 v227, 0xffff0000, v83
	v_mul_f32_e32 v220, v230, v220
	v_mul_f32_e32 v221, v230, v221
	v_mul_f32_e32 v222, v230, v222
	v_mul_f32_e32 v223, v230, v223
	v_mul_f32_e32 v224, v230, v224
	v_mul_f32_e32 v225, v230, v225
	v_mul_f32_e32 v226, v230, v226
	v_mul_f32_e32 v227, v230, v227
	v_fma_f32 v0, v229, v0, v220
	v_fma_f32 v1, v229, v1, v221
	v_fma_f32 v2, v229, v2, v222
	v_fma_f32 v3, v229, v3, v223
	v_fma_f32 v4, v229, v4, v224
	v_fma_f32 v5, v229, v5, v225
	v_fma_f32 v6, v229, v6, v226
	v_fma_f32 v7, v229, v7, v227
	s_add_i32 s13, s13, s10
	s_cmp_eq_u32 s13, s11
	s_cselect_b32 s13, s8, s13
	v_cvt_pk_bf16_f32 v216, v0, v1
	v_cvt_pk_bf16_f32 v217, v2, v3
	v_cvt_pk_bf16_f32 v218, v4, v5
	v_cvt_pk_bf16_f32 v219, v6, v7
	s_lshl_b32 s14, s13, 15
	s_add_u32 s16, s66, s14
	s_addc_u32 s17, s67, 0
	global_store_dwordx4 v236, v[216:219], s[16:17]
	v_readlane_b32 s18, v232, 63
	v_readlane_b32 s19, v233, 63
	s_nop 1
	v_add_f32_e32 v231, s18, v228
	v_max_f32_e32 v228, s19, v231
	v_sub_f32_e32 v231, v231, v228
	v_sub_f32_e32 v229, s19, v228
	v_mul_f32_e32 v231, 0x3fb8aa3b, v231
	v_mul_f32_e32 v229, 0x3fb8aa3b, v229
	v_exp_f32_e32 v230, v229
	v_exp_f32_e32 v229, v231
	s_nop 0
	v_lshlrev_b32_e32 v220, 16, v84
	v_and_b32_e32 v221, 0xffff0000, v84
	v_lshlrev_b32_e32 v222, 16, v85
	v_and_b32_e32 v223, 0xffff0000, v85
	v_lshlrev_b32_e32 v224, 16, v86
	v_and_b32_e32 v225, 0xffff0000, v86
	v_lshlrev_b32_e32 v226, 16, v87
	v_and_b32_e32 v227, 0xffff0000, v87
	v_mul_f32_e32 v220, v230, v220
	v_mul_f32_e32 v221, v230, v221
	v_mul_f32_e32 v222, v230, v222
	v_mul_f32_e32 v223, v230, v223
	v_mul_f32_e32 v224, v230, v224
	v_mul_f32_e32 v225, v230, v225
	v_mul_f32_e32 v226, v230, v226
	v_mul_f32_e32 v227, v230, v227
	v_fma_f32 v0, v229, v0, v220
	v_fma_f32 v1, v229, v1, v221
	v_fma_f32 v2, v229, v2, v222
	v_fma_f32 v3, v229, v3, v223
	v_fma_f32 v4, v229, v4, v224
	v_fma_f32 v5, v229, v5, v225
	v_fma_f32 v6, v229, v6, v226
	v_fma_f32 v7, v229, v7, v227
	s_add_i32 s13, s13, s10
	s_cmp_eq_u32 s13, s11
	s_cselect_b32 s13, s8, s13
	v_cvt_pk_bf16_f32 v216, v0, v1
	v_cvt_pk_bf16_f32 v217, v2, v3
	v_cvt_pk_bf16_f32 v218, v4, v5
	v_cvt_pk_bf16_f32 v219, v6, v7
	s_lshl_b32 s14, s13, 15
	s_add_u32 s16, s66, s14
	s_addc_u32 s17, s67, 0
	global_store_dwordx4 v236, v[216:219], s[16:17]
	v_readlane_b32 s18, v234, 0
	v_readlane_b32 s19, v235, 0
	s_nop 1
	v_add_f32_e32 v231, s18, v228
	v_max_f32_e32 v228, s19, v231
	v_sub_f32_e32 v231, v231, v228
	v_sub_f32_e32 v229, s19, v228
	v_mul_f32_e32 v231, 0x3fb8aa3b, v231
	v_mul_f32_e32 v229, 0x3fb8aa3b, v229
	v_exp_f32_e32 v230, v229
	v_exp_f32_e32 v229, v231
	s_nop 0
	v_lshlrev_b32_e32 v220, 16, v88
	v_and_b32_e32 v221, 0xffff0000, v88
	v_lshlrev_b32_e32 v222, 16, v89
	v_and_b32_e32 v223, 0xffff0000, v89
	v_lshlrev_b32_e32 v224, 16, v90
	v_and_b32_e32 v225, 0xffff0000, v90
	v_lshlrev_b32_e32 v226, 16, v91
	v_and_b32_e32 v227, 0xffff0000, v91
	v_mul_f32_e32 v220, v230, v220
	v_mul_f32_e32 v221, v230, v221
	v_mul_f32_e32 v222, v230, v222
	v_mul_f32_e32 v223, v230, v223
	v_mul_f32_e32 v224, v230, v224
	v_mul_f32_e32 v225, v230, v225
	v_mul_f32_e32 v226, v230, v226
	v_mul_f32_e32 v227, v230, v227
	v_fma_f32 v0, v229, v0, v220
	v_fma_f32 v1, v229, v1, v221
	v_fma_f32 v2, v229, v2, v222
	v_fma_f32 v3, v229, v3, v223
	v_fma_f32 v4, v229, v4, v224
	v_fma_f32 v5, v229, v5, v225
	v_fma_f32 v6, v229, v6, v226
	v_fma_f32 v7, v229, v7, v227
	s_add_i32 s13, s13, s10
	s_cmp_eq_u32 s13, s11
	s_cselect_b32 s13, s8, s13
	v_cvt_pk_bf16_f32 v216, v0, v1
	v_cvt_pk_bf16_f32 v217, v2, v3
	v_cvt_pk_bf16_f32 v218, v4, v5
	v_cvt_pk_bf16_f32 v219, v6, v7
	s_lshl_b32 s14, s13, 15
	s_add_u32 s16, s66, s14
	s_addc_u32 s17, s67, 0
	global_store_dwordx4 v236, v[216:219], s[16:17]
	v_readlane_b32 s18, v234, 1
	v_readlane_b32 s19, v235, 1
	s_nop 1
	v_add_f32_e32 v231, s18, v228
	v_max_f32_e32 v228, s19, v231
	v_sub_f32_e32 v231, v231, v228
	v_sub_f32_e32 v229, s19, v228
	v_mul_f32_e32 v231, 0x3fb8aa3b, v231
	v_mul_f32_e32 v229, 0x3fb8aa3b, v229
	v_exp_f32_e32 v230, v229
	v_exp_f32_e32 v229, v231
	s_nop 0
	v_lshlrev_b32_e32 v220, 16, v92
	v_and_b32_e32 v221, 0xffff0000, v92
	v_lshlrev_b32_e32 v222, 16, v93
	v_and_b32_e32 v223, 0xffff0000, v93
	v_lshlrev_b32_e32 v224, 16, v94
	v_and_b32_e32 v225, 0xffff0000, v94
	v_lshlrev_b32_e32 v226, 16, v95
	v_and_b32_e32 v227, 0xffff0000, v95
	v_mul_f32_e32 v220, v230, v220
	v_mul_f32_e32 v221, v230, v221
	v_mul_f32_e32 v222, v230, v222
	v_mul_f32_e32 v223, v230, v223
	v_mul_f32_e32 v224, v230, v224
	v_mul_f32_e32 v225, v230, v225
	v_mul_f32_e32 v226, v230, v226
	v_mul_f32_e32 v227, v230, v227
	v_fma_f32 v0, v229, v0, v220
	v_fma_f32 v1, v229, v1, v221
	v_fma_f32 v2, v229, v2, v222
	v_fma_f32 v3, v229, v3, v223
	v_fma_f32 v4, v229, v4, v224
	v_fma_f32 v5, v229, v5, v225
	v_fma_f32 v6, v229, v6, v226
	v_fma_f32 v7, v229, v7, v227
	s_add_i32 s13, s13, s10
	s_cmp_eq_u32 s13, s11
	s_cselect_b32 s13, s8, s13
	s_add_u32 s76, s76, s77
	s_cmp_lt_u32 s76, 1024
	s_cbranch_scc1 .Lgs_unit
	s_branch .Lgs_done
